# conv-FFN up-projection GEMM k-loops (both layers) rewritten as the 8-phase schedule: SGPR-base LDS-DMA, EXEC-masked halo rows with zero-filled LDS rows
# speedup vs baseline: 1.0257x; 1.0141x over previous
; template <bool SWAP>
; DI void gemm_mainloop(f32x16 (&acc)[4][2], const u16* __restrict__ A, int lda, int rlo, int rhi,
;                       const u16* __restrict__ B, int ldb, int K, char* lds, const u16* zero_line) {
;     ...
;   const int gch = (lc ^ ((lr >> 1) & 7)) * 8;
;   const u16* ap = A + (ptrdiff_t)lr * lda + gch;
;   const u16* bp = B + (ptrdiff_t)lr * ldb + gch;
;   const int nk = K >> 6;
;   typedef __attribute__((address_space(3))) unsigned lds_u32;
;   auto glds = [&](int kt, int st) {
;     char* as_ = lds + st * 65536 + tid * 16;
; #pragma unroll
;     for (int i = 0; i < 4; ++i) {
;       const int rr = lr + 64 * i;
;       const u16* srca = (rr >= rlo && rr < rhi) ? (ap + (ptrdiff_t)(64 * i) * lda + kt * 64) : (zero_line + lc * 8);
;       __builtin_amdgcn_global_load_lds((const unsigned*)srca, (lds_u32*)(as_ + i * 8192), 16, 0, 0);
;       __builtin_amdgcn_global_load_lds((const unsigned*)(bp + (ptrdiff_t)(64 * i) * ldb + kt * 64), (lds_u32*)(as_ + 32768 + i * 8192), 16, 0, 0);
;     }
;   };
;   const int sw = (r >> 1) & 7;
;   const int arow_off = (wm * 128 + r) * 128;
;   const int brow_off = 32768 + (wn * 64 + r) * 128;
;   __syncthreads();
;   glds(0, 0);
;   asm volatile("s_waitcnt vmcnt(0)" ::: "memory");
;   __syncthreads();
; template <int EPI>
; DI void phase_gemm(const Params& p, const GemmArgs& ga, char* lds) {
;     ...
;   for (int it = 0; it * (int)gridDim.x < total; ++it) {
;     const int lt = logical_index(it);
;     if (lt >= total) continue;
;     int mt, nt;
;     tile_mn(lt, Mt, ga.Nt, mt, nt);
;     int bb, tokbase, S, pos0, rlo = 0, rhi = 256;
;     if (EPI == EPI_UP) {
;       bb = 0; tokbase = 0; S = NTOK;
;       pos0 = 254 * mt - 1;
;       rlo = (mt == 0) ? 1 : 0;
;       rhi = NTOK - pos0; if (rhi > 256) rhi = 256;
;     } else {
;       seq_of_token(mt * 256, bb, tokbase, S);
;       pos0 = mt * 256 - tokbase;
;     }
;     const u16* A = ga.A + (ptrdiff_t)(tokbase + pos0) * ga.lda;
;     const u16* B = ga.Bt + (size_t)(nt * 256) * ga.K;
.LBB0_56:
	s_add_i32 s30, s10, s25
	s_cmpk_gt_i32 s30, 0x10ab
	s_cbranch_scc1 .LBB0_55
	s_mul_hi_i32 s10, s30, 0x2e8ba2e9
	s_lshr_b32 s11, s10, 31
	s_ashr_i32 s10, s10, 5
	s_add_i32 s31, s10, s11
	s_lshl_b32 s10, s31, 3
	s_sub_i32 s11, 0xc2, s10
	s_min_u32 s11, s11, 8
	v_cvt_f32_ubyte0_e32 v0, s11
	v_rcp_iflag_f32_e32 v0, v0
	s_sub_i32 s15, 0, s11
	s_mul_i32 s12, s31, 0xffffff50
	s_add_i32 s12, s12, s30
	v_mul_f32_e32 v0, 0x4f7ffffe, v0
	v_cvt_u32_f32_e32 v0, v0
	s_abs_i32 s14, s12
	s_ashr_i32 s13, s12, 31
	s_waitcnt vmcnt(5)
	v_mov_b32_e32 v13, v204
	v_readfirstlane_b32 s16, v0
	s_mul_i32 s15, s15, s16
	s_mul_hi_u32 s15, s16, s15
	s_add_i32 s16, s16, s15
	s_mul_hi_u32 s15, s14, s16
	s_mul_i32 s16, s15, s11
	s_sub_i32 s14, s14, s16
	s_add_i32 s16, s15, 1
	s_sub_i32 s17, s14, s11
	s_cmp_ge_u32 s14, s11
	s_cselect_b32 s15, s16, s15
	s_cselect_b32 s14, s17, s14
	s_add_i32 s16, s15, 1
	s_cmp_ge_u32 s14, s11
	s_cselect_b32 s14, s16, s15
	s_xor_b32 s14, s14, s13
	s_sub_i32 s28, s14, s13
	s_mul_i32 s34, s28, s11
	s_add_i32 s14, s12, s10
	s_sub_i32 s27, s14, s34
	s_mulk_i32 s27, 0xfe
	s_lshl_b32 s10, s28, 8
	s_add_i32 s20, s27, -1
	s_ashr_i32 s11, s10, 31
	s_ashr_i32 s21, s20, 31
	s_lshl_b64 s[22:23], s[10:11], 11
	v_readlane_b32 s10, v253, 17
	v_readlane_b32 s11, v253, 18
	s_add_u32 s10, s10, s22
	s_addc_u32 s11, s11, s23
	s_lshl_b64 s[12:13], s[20:21], 11
	s_add_u32 s12, s90, s12
	v_ashrrev_i32_e32 v2, 3, v13
	s_waitcnt vmcnt(4)
	v_lshrrev_b32_e32 v15, 1, v2
	s_addc_u32 s13, s91, s13
	s_sub_i32 s15, 0xc001, s27
	v_xor_b32_e32 v0, v15, v13
	v_ashrrev_i32_e32 v3, 31, v2
	s_min_i32 s18, s15, 0x100
	v_lshlrev_b64 v[4:5], 11, v[2:3]
	v_lshlrev_b32_e32 v0, 4, v0
	s_cmp_eq_u32 s14, s34
	v_and_b32_e32 v10, 31, v13
	v_lshl_add_u64 v[6:7], s[12:13], 0, v[4:5]
	v_and_b32_e32 v0, 0x70, v0
	v_lshl_add_u64 v[8:9], s[10:11], 0, v[4:5]
	v_lshrrev_b32_e32 v16, 1, v13
	s_cselect_b64 s[14:15], -1, 0
	v_lshl_add_u64 v[6:7], v[6:7], 0, v[0:1]
	v_lshl_add_u64 v[8:9], v[8:9], 0, v[0:1]
	v_and_or_b32 v0, v16, s51, v10
	v_cndmask_b32_e64 v12, 0, 1, s[14:15]
	v_lshlrev_b32_e32 v175, 7, v0
	v_lshlrev_b32_e32 v0, 7, v13
	v_lshlrev_b32_e32 v177, 4, v13
	v_and_b32_e32 v176, 0x6f80, v0
	v_cmp_ge_i32_e64 s[10:11], v2, v12
	v_cmp_gt_i32_e64 s[12:13], s18, v2
	v_and_b32_e32 v0, 0x70, v177
	v_add_u32_e32 v178, 0x8000, v177
	v_lshl_add_u64 v[158:159], s[80:81], 0, v[0:1]
	s_and_b64 s[10:11], s[10:11], s[12:13]
	v_readfirstlane_b32 s12, v177
	v_cndmask_b32_e64 v11, v159, v7, s[10:11]
	v_cndmask_b32_e64 v10, v158, v6, s[10:11]
	s_mov_b32 m0, s12
	v_readfirstlane_b32 s12, v178
	v_add_u32_e32 v0, 64, v2
	s_barrier
	s_mov_b32 m0, s12
	v_cmp_ge_i32_e64 s[12:13], v0, v12
	v_cmp_gt_i32_e64 s[14:15], s18, v0
	s_mov_b64 s[16:17], 0x20000
	v_add_u32_e32 v0, 0x2000, v177
	v_lshl_add_u64 v[10:11], v[6:7], 0, s[16:17]
	s_and_b64 s[12:13], s[12:13], s[14:15]
	v_readfirstlane_b32 s14, v0
	v_add_u32_e32 v179, 0xa000, v177
	v_cndmask_b32_e64 v11, v159, v11, s[12:13]
	v_cndmask_b32_e64 v10, v158, v10, s[12:13]
	s_mov_b32 m0, s14
	v_readfirstlane_b32 s14, v179
	v_add_u32_e32 v3, 0x80, v2
	v_lshl_add_u64 v[10:11], v[8:9], 0, s[16:17]
	s_mov_b32 m0, s14
	v_cmp_ge_i32_e64 s[14:15], v3, v12
	v_cmp_gt_i32_e64 s[16:17], s18, v3
	s_mov_b64 s[38:39], 0x40000
	v_add_u32_e32 v180, 0x4000, v177
	v_lshl_add_u64 v[10:11], v[6:7], 0, s[38:39]
	s_and_b64 s[14:15], s[14:15], s[16:17]
	v_readfirstlane_b32 s16, v180
	v_add_u32_e32 v181, 0xc000, v177
	v_cndmask_b32_e64 v11, v159, v11, s[14:15]
	v_cndmask_b32_e64 v10, v158, v10, s[14:15]
	s_mov_b32 m0, s16
	v_readfirstlane_b32 s16, v181
	v_add_u32_e32 v2, 0xc0, v2
	v_lshl_add_u64 v[10:11], v[8:9], 0, s[38:39]
	s_mov_b32 m0, s16
	v_cmp_ge_i32_e64 s[16:17], v2, v12
	v_cmp_gt_i32_e64 s[18:19], s18, v2
	s_mov_b64 s[38:39], 0x60000
	v_add_u32_e32 v182, 0x6000, v177
	v_lshl_add_u64 v[2:3], v[6:7], 0, s[38:39]
	s_and_b64 s[16:17], s[16:17], s[18:19]
	v_readfirstlane_b32 s18, v182
	v_add_u32_e32 v183, 0xe000, v177
	v_cndmask_b32_e64 v3, v159, v3, s[16:17]
	v_cndmask_b32_e64 v2, v158, v2, s[16:17]
	s_mov_b32 m0, s18
	v_readfirstlane_b32 s18, v183
	v_lshl_add_u64 v[2:3], v[8:9], 0, s[38:39]
	s_mov_b32 m0, s18
	s_sub_i32 s18, s30, s34
	s_mulk_i32 s31, 0xa8
	v_bfe_u32 v14, v13, 5, 1
	s_sub_i32 s18, s18, s31
	v_bfe_u32 v17, v13, 1, 3
	v_bitop3_b32 v2, v16, v14, 7 bitop3:0x6c
	s_mulk_i32 s18, 0xfe
	v_lshlrev_b32_e32 v185, 4, v2
	v_bitop3_b32 v2, v14, v17, 2 bitop3:0x36
	s_add_i32 s18, s18, -2
	v_lshlrev_b32_e32 v186, 4, v2
	v_bitop3_b32 v2, v14, v17, 4 bitop3:0x36
	s_ashr_i32 s19, s18, 31
	v_lshlrev_b32_e32 v187, 4, v2
	v_bitop3_b32 v2, v14, v17, 6 bitop3:0x36
	s_lshl_b64 s[18:19], s[18:19], 11
	v_bitop3_b32 v6, v15, 7, v13 bitop3:0x48
	v_lshlrev_b32_e32 v188, 4, v2
	v_lshl_add_u64 v[2:3], v[4:5], 0, s[18:19]
	v_lshlrev_b32_e32 v6, 4, v6
	v_or_b32_e32 v2, v2, v6
	v_lshl_add_u64 v[160:161], s[70:71], 0, v[2:3]
	v_lshl_add_u64 v[2:3], v[4:5], 0, s[22:23]
	s_waitcnt vmcnt(0)
	v_or_b32_e32 v2, v2, v6
	v_lshl_add_u64 v[162:163], s[70:71], 0, v[2:3]
	v_mov_b32_e32 v130, 0
	v_mov_b32_e32 v2, 0
	s_mov_b32 s29, 1
	s_mov_b64 s[38:39], 0x3858900
	v_add_u32_e32 v189, 0x10000, v177
	v_add_u32_e32 v190, 0x18000, v177
	v_add_u32_e32 v191, 0x12000, v177
	v_add_u32_e32 v192, 0x1a000, v177
	v_add_u32_e32 v193, 0x14000, v177
	v_add_u32_e32 v194, 0x1c000, v177
	v_add_u32_e32 v195, 0x16000, v177
	v_add_u32_e32 v196, 0x1e000, v177
	v_add_u32_e32 v197, 0x10000, v175
	v_or_b32_e32 v198, 0x10000, v176
	s_mov_b64 s[18:19], 0
	v_mov_b32_e32 v3, v2
	v_mov_b32_e32 v4, v2
	v_mov_b32_e32 v5, v2
	v_mov_b32_e32 v6, v2
	v_mov_b32_e32 v7, v2
	v_mov_b32_e32 v8, v2
	v_mov_b32_e32 v9, v2
	v_mov_b32_e32 v10, v2
	v_mov_b32_e32 v11, v2
	v_mov_b32_e32 v12, v2
	v_mov_b32_e32 v13, v2
	v_mov_b32_e32 v14, v2
	v_mov_b32_e32 v15, v2
	v_mov_b32_e32 v16, v2
	v_mov_b32_e32 v17, v2
	s_waitcnt vmcnt(0)
; template <bool SWAP>
; DI void gemm_mainloop(f32x16 (&acc)[4][2], const u16* __restrict__ A, int lda, int rlo, int rhi,
;                       const u16* __restrict__ B, int ldb, int K, char* lds, const u16* zero_line) {
;     ...
; #pragma unroll
;   for (int mi = 0; mi < 4; ++mi)
; #pragma unroll
;     for (int ni = 0; ni < 2; ++ni)
; #pragma unroll
;       for (int i = 0; i < 16; ++i) acc[mi][ni][i] = 0.f;
;   const int gch = (lc ^ ((lr >> 1) & 7)) * 8;
;   const u16* ap = A + (ptrdiff_t)lr * lda + gch;
;   const u16* bp = B + (ptrdiff_t)lr * ldb + gch;
;   const int nk = K >> 6;
;   typedef __attribute__((address_space(3))) unsigned lds_u32;
;   auto glds = [&](int kt, int st) {
;     char* as_ = lds + st * 65536 + tid * 16;
; #pragma unroll
;     for (int i = 0; i < 4; ++i) {
;       const int rr = lr + 64 * i;
;       const u16* srca = (rr >= rlo && rr < rhi) ? (ap + (ptrdiff_t)(64 * i) * lda + kt * 64) : (zero_line + lc * 8);
;       __builtin_amdgcn_global_load_lds((const unsigned*)srca, (lds_u32*)(as_ + i * 8192), 16, 0, 0);
;       __builtin_amdgcn_global_load_lds((const unsigned*)(bp + (ptrdiff_t)(64 * i) * ldb + kt * 64), (lds_u32*)(as_ + 32768 + i * 8192), 16, 0, 0);
;     }
;   };
;   const int sw = (r >> 1) & 7;
;   const int arow_off = (wm * 128 + r) * 128;
;   const int brow_off = 32768 + (wn * 64 + r) * 128;
;   __syncthreads();
;   glds(0, 0);
;   asm volatile("s_waitcnt vmcnt(0)" ::: "memory");
;   __syncthreads();
	v_mov_b32_e32 v18, v2
	v_mov_b32_e32 v19, v2
	v_mov_b32_e32 v20, v2
	v_mov_b32_e32 v21, v2
	v_mov_b32_e32 v22, v2
	v_mov_b32_e32 v23, v2
	v_mov_b32_e32 v24, v2
	v_mov_b32_e32 v25, v2
	v_mov_b32_e32 v26, v2
	v_mov_b32_e32 v27, v2
	v_mov_b32_e32 v28, v2
	v_mov_b32_e32 v29, v2
	v_mov_b32_e32 v30, v2
	v_mov_b32_e32 v31, v2
	v_mov_b32_e32 v32, v2
	v_mov_b32_e32 v33, v2
	v_mov_b32_e32 v34, v2
	v_mov_b32_e32 v35, v2
	v_mov_b32_e32 v36, v2
	v_mov_b32_e32 v37, v2
	v_mov_b32_e32 v38, v2
	v_mov_b32_e32 v39, v2
	v_mov_b32_e32 v40, v2
	v_mov_b32_e32 v41, v2
	v_mov_b32_e32 v42, v2
	v_mov_b32_e32 v43, v2
	v_mov_b32_e32 v44, v2
	v_mov_b32_e32 v45, v2
	v_mov_b32_e32 v46, v2
	v_mov_b32_e32 v47, v2
	v_mov_b32_e32 v48, v2
	v_mov_b32_e32 v49, v2
	v_mov_b32_e32 v50, v2
	v_mov_b32_e32 v51, v2
	v_mov_b32_e32 v52, v2
	v_mov_b32_e32 v53, v2
	v_mov_b32_e32 v54, v2
	v_mov_b32_e32 v55, v2
	v_mov_b32_e32 v56, v2
	v_mov_b32_e32 v57, v2
	v_mov_b32_e32 v58, v2
	v_mov_b32_e32 v59, v2
	v_mov_b32_e32 v60, v2
	v_mov_b32_e32 v61, v2
	v_mov_b32_e32 v62, v2
	v_mov_b32_e32 v63, v2
	v_mov_b32_e32 v64, v2
	v_mov_b32_e32 v65, v2
	v_mov_b32_e32 v66, v2
	v_mov_b32_e32 v67, v2
	v_mov_b32_e32 v68, v2
	v_mov_b32_e32 v69, v2
	v_mov_b32_e32 v70, v2
	v_mov_b32_e32 v71, v2
	v_mov_b32_e32 v72, v2
	v_mov_b32_e32 v73, v2
	v_mov_b32_e32 v74, v2
	v_mov_b32_e32 v75, v2
	v_mov_b32_e32 v76, v2
	v_mov_b32_e32 v77, v2
	v_mov_b32_e32 v78, v2
	v_mov_b32_e32 v79, v2
	v_mov_b32_e32 v80, v2
	v_mov_b32_e32 v81, v2
	v_mov_b32_e32 v82, v2
	v_mov_b32_e32 v83, v2
	v_mov_b32_e32 v84, v2
	v_mov_b32_e32 v85, v2
	v_mov_b32_e32 v86, v2
	v_mov_b32_e32 v87, v2
	v_mov_b32_e32 v88, v2
	v_mov_b32_e32 v89, v2
	v_mov_b32_e32 v90, v2
	v_mov_b32_e32 v91, v2
	v_mov_b32_e32 v92, v2
	v_mov_b32_e32 v93, v2
	v_mov_b32_e32 v94, v2
	v_mov_b32_e32 v95, v2
	v_mov_b32_e32 v96, v2
	v_mov_b32_e32 v97, v2
	v_mov_b32_e32 v98, v2
	v_mov_b32_e32 v99, v2
	v_mov_b32_e32 v100, v2
	v_mov_b32_e32 v101, v2
	v_mov_b32_e32 v102, v2
	v_mov_b32_e32 v103, v2
	v_mov_b32_e32 v104, v2
	v_mov_b32_e32 v105, v2
	v_mov_b32_e32 v106, v2
	v_mov_b32_e32 v107, v2
	v_mov_b32_e32 v108, v2
	v_mov_b32_e32 v109, v2
	v_mov_b32_e32 v110, v2
	v_mov_b32_e32 v111, v2
	v_mov_b32_e32 v112, v2
	v_mov_b32_e32 v113, v2
	v_mov_b32_e32 v114, v2
	v_mov_b32_e32 v115, v2
	v_mov_b32_e32 v116, v2
	v_mov_b32_e32 v117, v2
	v_mov_b32_e32 v118, v2
	v_mov_b32_e32 v119, v2
	v_mov_b32_e32 v120, v2
	v_mov_b32_e32 v121, v2
	v_mov_b32_e32 v122, v2
	v_mov_b32_e32 v123, v2
	v_mov_b32_e32 v124, v2
	v_mov_b32_e32 v125, v2
	v_mov_b32_e32 v126, v2
	v_mov_b32_e32 v127, v2
	v_mov_b32_e32 v128, v2
	v_mov_b32_e32 v129, v2
	v_mov_b32_e32 v131, v130
	v_mov_b32_e32 v132, v130
	v_mov_b32_e32 v133, v130
	v_mov_b32_e32 v134, v130
	v_mov_b32_e32 v135, v130
	v_mov_b32_e32 v136, v130
	v_mov_b32_e32 v137, v130
	v_mov_b32_e32 v138, v130
	v_mov_b32_e32 v139, v130
	v_mov_b32_e32 v140, v130
	v_mov_b32_e32 v141, v130
	v_mov_b32_e32 v142, v130
	v_mov_b32_e32 v143, v130
	v_mov_b32_e32 v144, v130
	v_mov_b32_e32 v145, v130
	v_mov_b32_e32 v146, v130
	v_mov_b32_e32 v147, v130
	v_mov_b32_e32 v148, v130
	v_mov_b32_e32 v149, v130
	v_mov_b32_e32 v150, v130
	v_mov_b32_e32 v151, v130
	v_mov_b32_e32 v152, v130
	v_mov_b32_e32 v153, v130
	s_mov_b64 s[30:31], 0x37f8900
	s_waitcnt vmcnt(0) lgkmcnt(0)
	s_barrier
	s_add_i32 s18, s27, -1
	s_ashr_i32 s19, s18, 31
	s_lshl_b64 s[18:19], s[18:19], 11
	s_add_u32 s18, s90, s18
	s_addc_u32 s19, s91, s19
	v_readlane_b32 s22, v253, 17
	v_readlane_b32 s23, v253, 18
	s_lshl_b32 s21, s28, 19
	s_add_u32 s22, s22, s21
	s_addc_u32 s23, s23, 0
	v_and_b32_e32 v130, 63, v204
	v_lshrrev_b32_e32 v131, 6, v204
	v_lshrrev_b32_e32 v132, 3, v204
	v_lshrrev_b32_e32 v0, 4, v130
	v_lshl_add_u32 v0, v131, 2, v0
	v_xor_b32_e32 v0, v0, v130
	v_and_b32_e32 v0, 7, v0
	v_lshlrev_b32_e32 v133, 4, v0
	v_lshl_add_u32 v236, v132, 11, v133
	v_add_u32_e32 v237, 0x20000, v236
	v_add_u32_e32 v238, 0x40000, v236
	v_add_u32_e32 v239, 0x60000, v236
	v_and_b32_e32 v0, 31, v132
	v_lshrrev_b32_e32 v130, 5, v132
	v_lshl_add_u32 v0, v130, 6, v0
	v_lshl_add_u32 v240, v0, 11, v133
	v_add_u32_e32 v241, 0x10000, v240
	v_add_u32_e32 v242, 0x40000, v240
	v_add_u32_e32 v243, 0x50000, v240
	v_and_b32_e32 v132, 31, v204
	v_lshrrev_b32_e32 v0, 2, v131
	v_lshl_add_u32 v0, v0, 6, v132
	v_lshlrev_b32_e32 v248, 7, v0
	v_and_b32_e32 v0, 3, v131
	v_lshl_add_u32 v0, v0, 5, v132
	v_lshlrev_b32_e32 v249, 7, v0
	v_bfe_u32 v0, v204, 5, 1
	v_bfe_u32 v130, v132, 1, 3
	v_or_b32_e32 v133, 0, v0
	v_xor_b32_e32 v133, v133, v130
	v_lshlrev_b32_e32 v244, 4, v133
	v_or_b32_e32 v133, 2, v0
	v_xor_b32_e32 v133, v133, v130
	v_lshlrev_b32_e32 v245, 4, v133
	v_or_b32_e32 v133, 4, v0
	v_xor_b32_e32 v133, v133, v130
	v_lshlrev_b32_e32 v246, 4, v133
	v_or_b32_e32 v133, 6, v0
	v_xor_b32_e32 v133, v133, v130
	v_lshlrev_b32_e32 v247, 4, v133
	v_lshlrev_b32_e32 v131, 10, v131
	s_nop 0
	v_readfirstlane_b32 s100, v131
	v_mov_b32_e32 v146, 0
	v_mov_b32_e32 v147, 0
	v_mov_b32_e32 v148, 0
	v_mov_b32_e32 v149, 0
	v_lshlrev_b32_e32 v130, 4, v204
	v_add_u32_e32 v132, 0x10000, v130
	s_not_b64 exec, s[10:11]
	ds_write_b128 v130, v[146:149]
	ds_write_b128 v132, v[146:149]
	s_not_b64 exec, s[12:13]
	ds_write_b128 v130, v[146:149] offset:16384
	ds_write_b128 v132, v[146:149] offset:16384
	s_not_b64 exec, s[14:15]
	ds_write_b128 v130, v[146:149] offset:8192
	ds_write_b128 v132, v[146:149] offset:8192
	s_not_b64 exec, s[16:17]
	ds_write_b128 v130, v[146:149] offset:24576
	ds_write_b128 v132, v[146:149] offset:24576
	s_mov_b64 exec, -1
	s_mov_b32 s29, 0
	s_mov_b32 s21, 0x10000
	s_waitcnt lgkmcnt(0)
	s_add_u32 m0, s100, 0x8000
	s_nop 0
	global_load_lds_dwordx4 v240, s[22:23]
	v_add_u32_e32 v240, 0x80, v240
	s_add_u32 m0, s100, 0xa000
	s_nop 0
	global_load_lds_dwordx4 v242, s[22:23]
	v_add_u32_e32 v242, 0x80, v242
	s_add_u32 m0, s100, 0x0
	s_mov_b64 exec, s[10:11]
	global_load_lds_dwordx4 v236, s[18:19]
	s_mov_b64 exec, -1
	v_add_u32_e32 v236, 0x80, v236
	s_add_u32 m0, s100, 0x2000
	s_mov_b64 exec, s[14:15]
	global_load_lds_dwordx4 v238, s[18:19]
	s_mov_b64 exec, -1
	v_add_u32_e32 v238, 0x80, v238
	s_add_u32 m0, s100, 0xc000
	s_nop 0
	global_load_lds_dwordx4 v241, s[22:23]
	v_add_u32_e32 v241, 0x80, v241
	s_add_u32 m0, s100, 0xe000
	s_nop 0
	global_load_lds_dwordx4 v243, s[22:23]
	v_add_u32_e32 v243, 0x80, v243
	s_add_u32 m0, s100, 0x4000
	s_mov_b64 exec, s[12:13]
	global_load_lds_dwordx4 v237, s[18:19]
	s_mov_b64 exec, -1
	v_add_u32_e32 v237, 0x80, v237
	s_add_u32 m0, s100, 0x6000
	s_mov_b64 exec, s[16:17]
	global_load_lds_dwordx4 v239, s[18:19]
	s_mov_b64 exec, -1
	v_add_u32_e32 v239, 0x80, v239
	s_cmp_eq_u32 s101, 1
	s_cbranch_scc0 .Lg8_u0_p0
	s_barrier
; #define MFMA(a, b, c) __builtin_amdgcn_mfma_f32_32x32x16_bf16((a), (b), (c), 0, 0, 0)
; template <bool SWAP>
; DI void gemm_mainloop(f32x16 (&acc)[4][2], const u16* __restrict__ A, int lda, int rlo, int rhi,
;                       const u16* __restrict__ B, int ldb, int K, char* lds, const u16* zero_line) {
;     ...
;   auto ldfrag = [&](const char* st, int ks, int buf) {
;     const int co = ((2 * ks + h) ^ sw) << 4;
; #pragma unroll
;     for (int mi = 0; mi < 4; ++mi) fa[buf][mi] = *(const bf16x8*)(st + arow_off + mi * 4096 + co);
; #pragma unroll
;     for (int ni = 0; ni < 2; ++ni) fb[buf][ni] = *(const bf16x8*)(st + brow_off + ni * 4096 + co);
;   };
;   auto mma = [&](int buf) {
; #pragma unroll
;     for (int mi = 0; mi < 4; ++mi)
; #pragma unroll
;       for (int ni = 0; ni < 2; ++ni)
;         acc[mi][ni] = SWAP ? MFMA(fb[buf][ni], fa[buf][mi], acc[mi][ni]) : MFMA(fa[buf][mi], fb[buf][ni], acc[mi][ni]);
;   };
;   auto pat_rd = [&]() {
; #pragma unroll
;     for (int g = 0; g < 6; ++g) {
;       __builtin_amdgcn_sched_group_barrier(0x100, 1, 0);
;       __builtin_amdgcn_sched_group_barrier(0x008, 1, 0);
;     }
;     __builtin_amdgcn_sched_group_barrier(0x008, 2, 0);
;   };
; #pragma unroll 2
;   for (int kt = 0; kt < nk; ++kt) {
;     const char* st = lds + (kt & 1) * 65536;
;     ldfrag(st, 0, 0);
;     mma(1);
;     pat_rd();
;     if (kt + 1 < nk) glds(kt + 1, (kt + 1) & 1);
;     ldfrag(st, 1, 1);
;     mma(0);
;     pat_rd();
;     ldfrag(st, 2, 0);
;     mma(1);
;     pat_rd();
;     ldfrag(st, 3, 1);
;     mma(0);
;     pat_rd();
;     asm volatile("s_waitcnt vmcnt(0)" ::: "memory");
;     __syncthreads();
.Lg8_u0_p0:
	s_waitcnt vmcnt(4)
	s_barrier
	s_add_u32 m0, s100, 0x18000
	s_nop 0
	global_load_lds_dwordx4 v240, s[22:23]
	v_add_u32_e32 v240, 0x80, v240
	s_add_u32 m0, s100, 0x1a000
	s_nop 0
	global_load_lds_dwordx4 v242, s[22:23]
	v_add_u32_e32 v242, 0x80, v242
	s_add_u32 m0, s100, 0x10000
	s_mov_b64 exec, s[10:11]
	global_load_lds_dwordx4 v236, s[18:19]
	s_mov_b64 exec, -1
	v_add_u32_e32 v236, 0x80, v236
	s_add_u32 m0, s100, 0x12000
	s_mov_b64 exec, s[14:15]
	global_load_lds_dwordx4 v238, s[18:19]
	s_mov_b64 exec, -1
	v_add_u32_e32 v238, 0x80, v238
	s_add_u32 m0, s100, 0x1c000
	s_nop 0
	global_load_lds_dwordx4 v241, s[22:23]
	v_add_u32_e32 v241, 0x80, v241
	s_add_u32 m0, s100, 0x1e000
	s_nop 0
	global_load_lds_dwordx4 v243, s[22:23]
	v_add_u32_e32 v243, 0x80, v243
	s_waitcnt vmcnt(6)
	s_barrier
.Lg8_u0:
	v_add3_u32 v166, v249, v244, 0
	v_add3_u32 v167, v249, v245, 0
	v_add3_u32 v175, v249, v246, 0
	v_add3_u32 v185, v249, v247, 0
	ds_read_b128 v[176:179], v166 offset:32768
	ds_read_b128 v[180:183], v167 offset:32768
	ds_read_b128 v[186:189], v175 offset:32768
	ds_read_b128 v[190:193], v185 offset:32768
	v_add3_u32 v166, v248, v244, 0
	v_add3_u32 v167, v248, v245, 0
	v_add3_u32 v175, v248, v246, 0
	v_add3_u32 v185, v248, v247, 0
	ds_read_b128 v[130:133], v166
	ds_read_b128 v[134:137], v167
	ds_read_b128 v[138:141], v175
	ds_read_b128 v[142:145], v185
	ds_read_b128 v[146:149], v166 offset:4096
	ds_read_b128 v[150:153], v167 offset:4096
	ds_read_b128 v[158:161], v175 offset:4096
	ds_read_b128 v[162:165], v185 offset:4096
	s_add_u32 m0, s100, 0x14000
	s_mov_b64 exec, s[12:13]
	global_load_lds_dwordx4 v237, s[18:19]
	s_mov_b64 exec, -1
	v_add_u32_e32 v237, 0x80, v237
	s_add_u32 m0, s100, 0x16000
	s_mov_b64 exec, s[16:17]
	global_load_lds_dwordx4 v239, s[18:19]
	s_mov_b64 exec, -1
	v_add_u32_e32 v239, 0x80, v239
	s_waitcnt lgkmcnt(8)
	s_barrier
	s_waitcnt lgkmcnt(0)
	v_mfma_f32_32x32x16_bf16 v[114:129], v[176:179], v[130:133], v[114:129]
	v_mfma_f32_32x32x16_bf16 v[82:97], v[176:179], v[146:149], v[82:97]
	v_mfma_f32_32x32x16_bf16 v[114:129], v[180:183], v[134:137], v[114:129]
	v_mfma_f32_32x32x16_bf16 v[82:97], v[180:183], v[150:153], v[82:97]
	v_mfma_f32_32x32x16_bf16 v[114:129], v[186:189], v[138:141], v[114:129]
	v_mfma_f32_32x32x16_bf16 v[82:97], v[186:189], v[158:161], v[82:97]
	v_mfma_f32_32x32x16_bf16 v[114:129], v[190:193], v[142:145], v[114:129]
	v_mfma_f32_32x32x16_bf16 v[82:97], v[190:193], v[162:165], v[82:97]
	s_barrier
	v_add3_u32 v166, v249, v244, 0
	v_add3_u32 v167, v249, v245, 0
	v_add3_u32 v175, v249, v246, 0
	v_add3_u32 v185, v249, v247, 0
	ds_read_b128 v[194:197], v166 offset:49152
	ds_read_b128 v[198:201], v167 offset:49152
	ds_read_b128 v[228:231], v175 offset:49152
	ds_read_b128 v[232:235], v185 offset:49152
	s_add_u32 m0, s100, 0x8000
	s_nop 0
	global_load_lds_dwordx4 v240, s[22:23]
	v_add_u32_e32 v240, 0x80, v240
	s_add_u32 m0, s100, 0xa000
	s_nop 0
	global_load_lds_dwordx4 v242, s[22:23]
	v_add_u32_e32 v242, 0x80, v242
	s_barrier
	s_waitcnt lgkmcnt(0)
	v_mfma_f32_32x32x16_bf16 v[98:113], v[194:197], v[130:133], v[98:113]
	v_mfma_f32_32x32x16_bf16 v[66:81], v[194:197], v[146:149], v[66:81]
	v_mfma_f32_32x32x16_bf16 v[98:113], v[198:201], v[134:137], v[98:113]
	v_mfma_f32_32x32x16_bf16 v[66:81], v[198:201], v[150:153], v[66:81]
	v_mfma_f32_32x32x16_bf16 v[98:113], v[228:231], v[138:141], v[98:113]
	v_mfma_f32_32x32x16_bf16 v[66:81], v[228:231], v[158:161], v[66:81]
	v_mfma_f32_32x32x16_bf16 v[98:113], v[232:235], v[142:145], v[98:113]
	v_mfma_f32_32x32x16_bf16 v[66:81], v[232:235], v[162:165], v[66:81]
	s_barrier
	v_add3_u32 v166, v248, v244, 0
	v_add3_u32 v167, v248, v245, 0
	v_add3_u32 v175, v248, v246, 0
	v_add3_u32 v185, v248, v247, 0
	ds_read_b128 v[130:133], v166 offset:16384
	ds_read_b128 v[134:137], v167 offset:16384
	ds_read_b128 v[138:141], v175 offset:16384
	ds_read_b128 v[142:145], v185 offset:16384
	ds_read_b128 v[146:149], v166 offset:20480
	ds_read_b128 v[150:153], v167 offset:20480
	ds_read_b128 v[158:161], v175 offset:20480
	ds_read_b128 v[162:165], v185 offset:20480
	s_add_u32 m0, s100, 0x0
	s_mov_b64 exec, s[10:11]
	global_load_lds_dwordx4 v236, s[18:19]
	s_mov_b64 exec, -1
	v_add_u32_e32 v236, 0x80, v236
	s_add_u32 m0, s100, 0x2000
	s_mov_b64 exec, s[14:15]
	global_load_lds_dwordx4 v238, s[18:19]
	s_mov_b64 exec, -1
	v_add_u32_e32 v238, 0x80, v238
	s_barrier
	s_waitcnt lgkmcnt(0)
	v_mfma_f32_32x32x16_bf16 v[50:65], v[176:179], v[130:133], v[50:65]
	v_mfma_f32_32x32x16_bf16 v[18:33], v[176:179], v[146:149], v[18:33]
	v_mfma_f32_32x32x16_bf16 v[50:65], v[180:183], v[134:137], v[50:65]
	v_mfma_f32_32x32x16_bf16 v[18:33], v[180:183], v[150:153], v[18:33]
	v_mfma_f32_32x32x16_bf16 v[50:65], v[186:189], v[138:141], v[50:65]
	v_mfma_f32_32x32x16_bf16 v[18:33], v[186:189], v[158:161], v[18:33]
	v_mfma_f32_32x32x16_bf16 v[50:65], v[190:193], v[142:145], v[50:65]
	v_mfma_f32_32x32x16_bf16 v[18:33], v[190:193], v[162:165], v[18:33]
	s_barrier
	s_add_u32 m0, s100, 0xc000
	s_nop 0
	global_load_lds_dwordx4 v241, s[22:23]
	v_add_u32_e32 v241, 0x80, v241
	s_add_u32 m0, s100, 0xe000
	s_nop 0
	global_load_lds_dwordx4 v243, s[22:23]
	v_add_u32_e32 v243, 0x80, v243
	s_waitcnt vmcnt(6)
	s_barrier
	v_mfma_f32_32x32x16_bf16 v[34:49], v[194:197], v[130:133], v[34:49]
	v_mfma_f32_32x32x16_bf16 v[2:17], v[194:197], v[146:149], v[2:17]
	v_mfma_f32_32x32x16_bf16 v[34:49], v[198:201], v[134:137], v[34:49]
	v_mfma_f32_32x32x16_bf16 v[2:17], v[198:201], v[150:153], v[2:17]
	v_mfma_f32_32x32x16_bf16 v[34:49], v[228:231], v[138:141], v[34:49]
	v_mfma_f32_32x32x16_bf16 v[2:17], v[228:231], v[158:161], v[2:17]
	v_mfma_f32_32x32x16_bf16 v[34:49], v[232:235], v[142:145], v[34:49]
	v_mfma_f32_32x32x16_bf16 v[2:17], v[232:235], v[162:165], v[2:17]
	s_barrier
; #define MFMA(a, b, c) __builtin_amdgcn_mfma_f32_32x32x16_bf16((a), (b), (c), 0, 0, 0)
; template <bool SWAP>
; DI void gemm_mainloop(f32x16 (&acc)[4][2], const u16* __restrict__ A, int lda, int rlo, int rhi,
;                       const u16* __restrict__ B, int ldb, int K, char* lds, const u16* zero_line) {
;     ...
;   auto ldfrag = [&](const char* st, int ks, int buf) {
;     const int co = ((2 * ks + h) ^ sw) << 4;
; #pragma unroll
;     for (int mi = 0; mi < 4; ++mi) fa[buf][mi] = *(const bf16x8*)(st + arow_off + mi * 4096 + co);
; #pragma unroll
;     for (int ni = 0; ni < 2; ++ni) fb[buf][ni] = *(const bf16x8*)(st + brow_off + ni * 4096 + co);
;   };
;   auto mma = [&](int buf) {
; #pragma unroll
;     for (int mi = 0; mi < 4; ++mi)
; #pragma unroll
;       for (int ni = 0; ni < 2; ++ni)
;         acc[mi][ni] = SWAP ? MFMA(fb[buf][ni], fa[buf][mi], acc[mi][ni]) : MFMA(fa[buf][mi], fb[buf][ni], acc[mi][ni]);
;   };
;   auto pat_rd = [&]() {
; #pragma unroll
;     for (int g = 0; g < 6; ++g) {
;       __builtin_amdgcn_sched_group_barrier(0x100, 1, 0);
;       __builtin_amdgcn_sched_group_barrier(0x008, 1, 0);
;     }
;     __builtin_amdgcn_sched_group_barrier(0x008, 2, 0);
;   };
; #pragma unroll 2
;   for (int kt = 0; kt < nk; ++kt) {
;     const char* st = lds + (kt & 1) * 65536;
;     ldfrag(st, 0, 0);
;     mma(1);
;     pat_rd();
;     if (kt + 1 < nk) glds(kt + 1, (kt + 1) & 1);
;     ldfrag(st, 1, 1);
;     mma(0);
;     pat_rd();
;     ldfrag(st, 2, 0);
;     mma(1);
;     pat_rd();
;     ldfrag(st, 3, 1);
;     mma(0);
;     pat_rd();
;     asm volatile("s_waitcnt vmcnt(0)" ::: "memory");
;     __syncthreads();
	v_add3_u32 v166, v249, v244, s21
	v_add3_u32 v167, v249, v245, s21
	v_add3_u32 v175, v249, v246, s21
	v_add3_u32 v185, v249, v247, s21
	ds_read_b128 v[176:179], v166 offset:32768
	ds_read_b128 v[180:183], v167 offset:32768
	ds_read_b128 v[186:189], v175 offset:32768
	ds_read_b128 v[190:193], v185 offset:32768
	v_add3_u32 v166, v248, v244, s21
	v_add3_u32 v167, v248, v245, s21
	v_add3_u32 v175, v248, v246, s21
	v_add3_u32 v185, v248, v247, s21
	ds_read_b128 v[130:133], v166
	ds_read_b128 v[134:137], v167
	ds_read_b128 v[138:141], v175
	ds_read_b128 v[142:145], v185
	ds_read_b128 v[146:149], v166 offset:4096
	ds_read_b128 v[150:153], v167 offset:4096
	ds_read_b128 v[158:161], v175 offset:4096
	ds_read_b128 v[162:165], v185 offset:4096
	s_add_u32 m0, s100, 0x4000
	s_mov_b64 exec, s[12:13]
	global_load_lds_dwordx4 v237, s[18:19]
	s_mov_b64 exec, -1
	v_add_u32_e32 v237, 0x80, v237
	s_add_u32 m0, s100, 0x6000
	s_mov_b64 exec, s[16:17]
	global_load_lds_dwordx4 v239, s[18:19]
	s_mov_b64 exec, -1
	v_add_u32_e32 v239, 0x80, v239
	s_waitcnt lgkmcnt(8)
	s_barrier
	s_waitcnt lgkmcnt(0)
	v_mfma_f32_32x32x16_bf16 v[114:129], v[176:179], v[130:133], v[114:129]
	v_mfma_f32_32x32x16_bf16 v[82:97], v[176:179], v[146:149], v[82:97]
	v_mfma_f32_32x32x16_bf16 v[114:129], v[180:183], v[134:137], v[114:129]
	v_mfma_f32_32x32x16_bf16 v[82:97], v[180:183], v[150:153], v[82:97]
	v_mfma_f32_32x32x16_bf16 v[114:129], v[186:189], v[138:141], v[114:129]
	v_mfma_f32_32x32x16_bf16 v[82:97], v[186:189], v[158:161], v[82:97]
	v_mfma_f32_32x32x16_bf16 v[114:129], v[190:193], v[142:145], v[114:129]
	v_mfma_f32_32x32x16_bf16 v[82:97], v[190:193], v[162:165], v[82:97]
	s_barrier
	v_add3_u32 v166, v249, v244, s21
	v_add3_u32 v167, v249, v245, s21
	v_add3_u32 v175, v249, v246, s21
	v_add3_u32 v185, v249, v247, s21
	ds_read_b128 v[194:197], v166 offset:49152
	ds_read_b128 v[198:201], v167 offset:49152
	ds_read_b128 v[228:231], v175 offset:49152
	ds_read_b128 v[232:235], v185 offset:49152
	s_add_u32 m0, s100, 0x18000
	s_nop 0
	global_load_lds_dwordx4 v240, s[22:23]
	v_add_u32_e32 v240, 0x80, v240
	s_add_u32 m0, s100, 0x1a000
	s_nop 0
	global_load_lds_dwordx4 v242, s[22:23]
	v_add_u32_e32 v242, 0x80, v242
	s_barrier
	s_waitcnt lgkmcnt(0)
	v_mfma_f32_32x32x16_bf16 v[98:113], v[194:197], v[130:133], v[98:113]
	v_mfma_f32_32x32x16_bf16 v[66:81], v[194:197], v[146:149], v[66:81]
	v_mfma_f32_32x32x16_bf16 v[98:113], v[198:201], v[134:137], v[98:113]
	v_mfma_f32_32x32x16_bf16 v[66:81], v[198:201], v[150:153], v[66:81]
	v_mfma_f32_32x32x16_bf16 v[98:113], v[228:231], v[138:141], v[98:113]
	v_mfma_f32_32x32x16_bf16 v[66:81], v[228:231], v[158:161], v[66:81]
	v_mfma_f32_32x32x16_bf16 v[98:113], v[232:235], v[142:145], v[98:113]
	v_mfma_f32_32x32x16_bf16 v[66:81], v[232:235], v[162:165], v[66:81]
	s_barrier
	v_add3_u32 v166, v248, v244, s21
	v_add3_u32 v167, v248, v245, s21
	v_add3_u32 v175, v248, v246, s21
	v_add3_u32 v185, v248, v247, s21
	ds_read_b128 v[130:133], v166 offset:16384
	ds_read_b128 v[134:137], v167 offset:16384
	ds_read_b128 v[138:141], v175 offset:16384
	ds_read_b128 v[142:145], v185 offset:16384
	ds_read_b128 v[146:149], v166 offset:20480
	ds_read_b128 v[150:153], v167 offset:20480
	ds_read_b128 v[158:161], v175 offset:20480
	ds_read_b128 v[162:165], v185 offset:20480
	s_add_u32 m0, s100, 0x10000
	s_mov_b64 exec, s[10:11]
	global_load_lds_dwordx4 v236, s[18:19]
	s_mov_b64 exec, -1
	v_add_u32_e32 v236, 0x80, v236
	s_add_u32 m0, s100, 0x12000
	s_mov_b64 exec, s[14:15]
	global_load_lds_dwordx4 v238, s[18:19]
	s_mov_b64 exec, -1
	v_add_u32_e32 v238, 0x80, v238
	s_barrier
	s_waitcnt lgkmcnt(0)
	v_mfma_f32_32x32x16_bf16 v[50:65], v[176:179], v[130:133], v[50:65]
	v_mfma_f32_32x32x16_bf16 v[18:33], v[176:179], v[146:149], v[18:33]
	v_mfma_f32_32x32x16_bf16 v[50:65], v[180:183], v[134:137], v[50:65]
	v_mfma_f32_32x32x16_bf16 v[18:33], v[180:183], v[150:153], v[18:33]
	v_mfma_f32_32x32x16_bf16 v[50:65], v[186:189], v[138:141], v[50:65]
	v_mfma_f32_32x32x16_bf16 v[18:33], v[186:189], v[158:161], v[18:33]
	v_mfma_f32_32x32x16_bf16 v[50:65], v[190:193], v[142:145], v[50:65]
	v_mfma_f32_32x32x16_bf16 v[18:33], v[190:193], v[162:165], v[18:33]
	s_barrier
	s_add_u32 m0, s100, 0x1c000
	s_nop 0
	global_load_lds_dwordx4 v241, s[22:23]
	v_add_u32_e32 v241, 0x80, v241
	s_add_u32 m0, s100, 0x1e000
	s_nop 0
	global_load_lds_dwordx4 v243, s[22:23]
	v_add_u32_e32 v243, 0x80, v243
	s_waitcnt vmcnt(6)
	s_barrier
	v_mfma_f32_32x32x16_bf16 v[34:49], v[194:197], v[130:133], v[34:49]
	v_mfma_f32_32x32x16_bf16 v[2:17], v[194:197], v[146:149], v[2:17]
	v_mfma_f32_32x32x16_bf16 v[34:49], v[198:201], v[134:137], v[34:49]
	v_mfma_f32_32x32x16_bf16 v[2:17], v[198:201], v[150:153], v[2:17]
	v_mfma_f32_32x32x16_bf16 v[34:49], v[228:231], v[138:141], v[34:49]
	v_mfma_f32_32x32x16_bf16 v[2:17], v[228:231], v[158:161], v[2:17]
	v_mfma_f32_32x32x16_bf16 v[34:49], v[232:235], v[142:145], v[34:49]
	v_mfma_f32_32x32x16_bf16 v[2:17], v[232:235], v[162:165], v[2:17]
	s_barrier
	s_add_i32 s29, s29, 2
	s_cmp_lt_u32 s29, 14
	s_cbranch_scc1 .Lg8_u0
	v_add3_u32 v166, v249, v244, 0
	v_add3_u32 v167, v249, v245, 0
	v_add3_u32 v175, v249, v246, 0
	v_add3_u32 v185, v249, v247, 0
	ds_read_b128 v[176:179], v166 offset:32768
	ds_read_b128 v[180:183], v167 offset:32768
	ds_read_b128 v[186:189], v175 offset:32768
	ds_read_b128 v[190:193], v185 offset:32768
	v_add3_u32 v166, v248, v244, 0
	v_add3_u32 v167, v248, v245, 0
	v_add3_u32 v175, v248, v246, 0
	v_add3_u32 v185, v248, v247, 0
	ds_read_b128 v[130:133], v166
	ds_read_b128 v[134:137], v167
	ds_read_b128 v[138:141], v175
	ds_read_b128 v[142:145], v185
	ds_read_b128 v[146:149], v166 offset:4096
	ds_read_b128 v[150:153], v167 offset:4096
	ds_read_b128 v[158:161], v175 offset:4096
	ds_read_b128 v[162:165], v185 offset:4096
	s_add_u32 m0, s100, 0x14000
	s_mov_b64 exec, s[12:13]
	global_load_lds_dwordx4 v237, s[18:19]
	s_mov_b64 exec, -1
	v_add_u32_e32 v237, 0x80, v237
	s_add_u32 m0, s100, 0x16000
	s_mov_b64 exec, s[16:17]
	global_load_lds_dwordx4 v239, s[18:19]
	s_mov_b64 exec, -1
	v_add_u32_e32 v239, 0x80, v239
	s_barrier
; #define MFMA(a, b, c) __builtin_amdgcn_mfma_f32_32x32x16_bf16((a), (b), (c), 0, 0, 0)
; template <bool SWAP>
; DI void gemm_mainloop(f32x16 (&acc)[4][2], const u16* __restrict__ A, int lda, int rlo, int rhi,
;                       const u16* __restrict__ B, int ldb, int K, char* lds, const u16* zero_line) {
;     ...
;   auto ldfrag = [&](const char* st, int ks, int buf) {
;     const int co = ((2 * ks + h) ^ sw) << 4;
; #pragma unroll
;     for (int mi = 0; mi < 4; ++mi) fa[buf][mi] = *(const bf16x8*)(st + arow_off + mi * 4096 + co);
; #pragma unroll
;     for (int ni = 0; ni < 2; ++ni) fb[buf][ni] = *(const bf16x8*)(st + brow_off + ni * 4096 + co);
;   };
;   auto mma = [&](int buf) {
; #pragma unroll
;     for (int mi = 0; mi < 4; ++mi)
; #pragma unroll
;       for (int ni = 0; ni < 2; ++ni)
;         acc[mi][ni] = SWAP ? MFMA(fb[buf][ni], fa[buf][mi], acc[mi][ni]) : MFMA(fa[buf][mi], fb[buf][ni], acc[mi][ni]);
;   };
;   auto pat_rd = [&]() {
; #pragma unroll
;     for (int g = 0; g < 6; ++g) {
;       __builtin_amdgcn_sched_group_barrier(0x100, 1, 0);
;       __builtin_amdgcn_sched_group_barrier(0x008, 1, 0);
;     }
;     __builtin_amdgcn_sched_group_barrier(0x008, 2, 0);
;   };
; #pragma unroll 2
;   for (int kt = 0; kt < nk; ++kt) {
;     const char* st = lds + (kt & 1) * 65536;
;     ldfrag(st, 0, 0);
;     mma(1);
;     pat_rd();
;     if (kt + 1 < nk) glds(kt + 1, (kt + 1) & 1);
;     ldfrag(st, 1, 1);
;     mma(0);
;     pat_rd();
;     ldfrag(st, 2, 0);
;     mma(1);
;     pat_rd();
;     ldfrag(st, 3, 1);
;     mma(0);
;     pat_rd();
;     asm volatile("s_waitcnt vmcnt(0)" ::: "memory");
;     __syncthreads();
;   }
;   mma(1);
	s_waitcnt lgkmcnt(0)
	v_mfma_f32_32x32x16_bf16 v[114:129], v[176:179], v[130:133], v[114:129]
	v_mfma_f32_32x32x16_bf16 v[82:97], v[176:179], v[146:149], v[82:97]
	v_mfma_f32_32x32x16_bf16 v[114:129], v[180:183], v[134:137], v[114:129]
	v_mfma_f32_32x32x16_bf16 v[82:97], v[180:183], v[150:153], v[82:97]
	v_mfma_f32_32x32x16_bf16 v[114:129], v[186:189], v[138:141], v[114:129]
	v_mfma_f32_32x32x16_bf16 v[82:97], v[186:189], v[158:161], v[82:97]
	v_mfma_f32_32x32x16_bf16 v[114:129], v[190:193], v[142:145], v[114:129]
	v_mfma_f32_32x32x16_bf16 v[82:97], v[190:193], v[162:165], v[82:97]
	s_barrier
	v_add3_u32 v166, v249, v244, 0
	v_add3_u32 v167, v249, v245, 0
	v_add3_u32 v175, v249, v246, 0
	v_add3_u32 v185, v249, v247, 0
	ds_read_b128 v[194:197], v166 offset:49152
	ds_read_b128 v[198:201], v167 offset:49152
	ds_read_b128 v[228:231], v175 offset:49152
	ds_read_b128 v[232:235], v185 offset:49152
	s_barrier
	s_waitcnt lgkmcnt(0)
	v_mfma_f32_32x32x16_bf16 v[98:113], v[194:197], v[130:133], v[98:113]
	v_mfma_f32_32x32x16_bf16 v[66:81], v[194:197], v[146:149], v[66:81]
	v_mfma_f32_32x32x16_bf16 v[98:113], v[198:201], v[134:137], v[98:113]
	v_mfma_f32_32x32x16_bf16 v[66:81], v[198:201], v[150:153], v[66:81]
	v_mfma_f32_32x32x16_bf16 v[98:113], v[228:231], v[138:141], v[98:113]
	v_mfma_f32_32x32x16_bf16 v[66:81], v[228:231], v[158:161], v[66:81]
	v_mfma_f32_32x32x16_bf16 v[98:113], v[232:235], v[142:145], v[98:113]
	v_mfma_f32_32x32x16_bf16 v[66:81], v[232:235], v[162:165], v[66:81]
	s_barrier
	v_add3_u32 v166, v248, v244, 0
	v_add3_u32 v167, v248, v245, 0
	v_add3_u32 v175, v248, v246, 0
	v_add3_u32 v185, v248, v247, 0
	ds_read_b128 v[130:133], v166 offset:16384
	ds_read_b128 v[134:137], v167 offset:16384
	ds_read_b128 v[138:141], v175 offset:16384
	ds_read_b128 v[142:145], v185 offset:16384
	ds_read_b128 v[146:149], v166 offset:20480
	ds_read_b128 v[150:153], v167 offset:20480
	ds_read_b128 v[158:161], v175 offset:20480
	ds_read_b128 v[162:165], v185 offset:20480
	s_waitcnt vmcnt(4)
	s_barrier
	s_waitcnt lgkmcnt(0)
	v_mfma_f32_32x32x16_bf16 v[50:65], v[176:179], v[130:133], v[50:65]
	v_mfma_f32_32x32x16_bf16 v[18:33], v[176:179], v[146:149], v[18:33]
	v_mfma_f32_32x32x16_bf16 v[50:65], v[180:183], v[134:137], v[50:65]
	v_mfma_f32_32x32x16_bf16 v[18:33], v[180:183], v[150:153], v[18:33]
	v_mfma_f32_32x32x16_bf16 v[50:65], v[186:189], v[138:141], v[50:65]
	v_mfma_f32_32x32x16_bf16 v[18:33], v[186:189], v[158:161], v[18:33]
	v_mfma_f32_32x32x16_bf16 v[50:65], v[190:193], v[142:145], v[50:65]
	v_mfma_f32_32x32x16_bf16 v[18:33], v[190:193], v[162:165], v[18:33]
	v_mfma_f32_32x32x16_bf16 v[34:49], v[194:197], v[130:133], v[34:49]
	v_mfma_f32_32x32x16_bf16 v[2:17], v[194:197], v[146:149], v[2:17]
	v_mfma_f32_32x32x16_bf16 v[34:49], v[198:201], v[134:137], v[34:49]
	v_mfma_f32_32x32x16_bf16 v[2:17], v[198:201], v[150:153], v[2:17]
	v_mfma_f32_32x32x16_bf16 v[34:49], v[228:231], v[138:141], v[34:49]
	v_mfma_f32_32x32x16_bf16 v[2:17], v[228:231], v[158:161], v[2:17]
	v_mfma_f32_32x32x16_bf16 v[34:49], v[232:235], v[142:145], v[34:49]
	v_mfma_f32_32x32x16_bf16 v[2:17], v[232:235], v[162:165], v[2:17]
	s_barrier
	v_add3_u32 v166, v249, v244, s21
	v_add3_u32 v167, v249, v245, s21
	v_add3_u32 v175, v249, v246, s21
	v_add3_u32 v185, v249, v247, s21
	ds_read_b128 v[176:179], v166 offset:32768
	ds_read_b128 v[180:183], v167 offset:32768
	ds_read_b128 v[186:189], v175 offset:32768
	ds_read_b128 v[190:193], v185 offset:32768
	v_add3_u32 v166, v248, v244, s21
	v_add3_u32 v167, v248, v245, s21
	v_add3_u32 v175, v248, v246, s21
	v_add3_u32 v185, v248, v247, s21
	ds_read_b128 v[130:133], v166
	ds_read_b128 v[134:137], v167
	ds_read_b128 v[138:141], v175
	ds_read_b128 v[142:145], v185
	ds_read_b128 v[146:149], v166 offset:4096
	ds_read_b128 v[150:153], v167 offset:4096
	ds_read_b128 v[158:161], v175 offset:4096
	ds_read_b128 v[162:165], v185 offset:4096
	s_waitcnt vmcnt(2)
	s_barrier
; #define MFMA(a, b, c) __builtin_amdgcn_mfma_f32_32x32x16_bf16((a), (b), (c), 0, 0, 0)
; template <bool SWAP>
; DI void gemm_mainloop(f32x16 (&acc)[4][2], const u16* __restrict__ A, int lda, int rlo, int rhi,
;                       const u16* __restrict__ B, int ldb, int K, char* lds, const u16* zero_line) {
;     ...
;   auto ldfrag = [&](const char* st, int ks, int buf) {
;     const int co = ((2 * ks + h) ^ sw) << 4;
; #pragma unroll
;     for (int mi = 0; mi < 4; ++mi) fa[buf][mi] = *(const bf16x8*)(st + arow_off + mi * 4096 + co);
; #pragma unroll
;     for (int ni = 0; ni < 2; ++ni) fb[buf][ni] = *(const bf16x8*)(st + brow_off + ni * 4096 + co);
;   };
;   auto mma = [&](int buf) {
; #pragma unroll
;     for (int mi = 0; mi < 4; ++mi)
; #pragma unroll
;       for (int ni = 0; ni < 2; ++ni)
;         acc[mi][ni] = SWAP ? MFMA(fb[buf][ni], fa[buf][mi], acc[mi][ni]) : MFMA(fa[buf][mi], fb[buf][ni], acc[mi][ni]);
;   };
;   auto pat_rd = [&]() {
; #pragma unroll
;     for (int g = 0; g < 6; ++g) {
;       __builtin_amdgcn_sched_group_barrier(0x100, 1, 0);
;       __builtin_amdgcn_sched_group_barrier(0x008, 1, 0);
;     }
;     __builtin_amdgcn_sched_group_barrier(0x008, 2, 0);
;   };
; #pragma unroll 2
;   for (int kt = 0; kt < nk; ++kt) {
;     const char* st = lds + (kt & 1) * 65536;
;     ldfrag(st, 0, 0);
;     mma(1);
;     pat_rd();
;     if (kt + 1 < nk) glds(kt + 1, (kt + 1) & 1);
;     ldfrag(st, 1, 1);
;     mma(0);
;     pat_rd();
;     ldfrag(st, 2, 0);
;     mma(1);
;     pat_rd();
;     ldfrag(st, 3, 1);
;     mma(0);
;     pat_rd();
;     asm volatile("s_waitcnt vmcnt(0)" ::: "memory");
;     __syncthreads();
;   }
;   mma(1);
	s_waitcnt lgkmcnt(0)
	v_mfma_f32_32x32x16_bf16 v[114:129], v[176:179], v[130:133], v[114:129]
	v_mfma_f32_32x32x16_bf16 v[82:97], v[176:179], v[146:149], v[82:97]
	v_mfma_f32_32x32x16_bf16 v[114:129], v[180:183], v[134:137], v[114:129]
	v_mfma_f32_32x32x16_bf16 v[82:97], v[180:183], v[150:153], v[82:97]
	v_mfma_f32_32x32x16_bf16 v[114:129], v[186:189], v[138:141], v[114:129]
	v_mfma_f32_32x32x16_bf16 v[82:97], v[186:189], v[158:161], v[82:97]
	v_mfma_f32_32x32x16_bf16 v[114:129], v[190:193], v[142:145], v[114:129]
	v_mfma_f32_32x32x16_bf16 v[82:97], v[190:193], v[162:165], v[82:97]
	s_barrier
	v_add3_u32 v166, v249, v244, s21
	v_add3_u32 v167, v249, v245, s21
	v_add3_u32 v175, v249, v246, s21
	v_add3_u32 v185, v249, v247, s21
	ds_read_b128 v[194:197], v166 offset:49152
	ds_read_b128 v[198:201], v167 offset:49152
	ds_read_b128 v[228:231], v175 offset:49152
	ds_read_b128 v[232:235], v185 offset:49152
	s_waitcnt vmcnt(0)
	s_barrier
	s_waitcnt lgkmcnt(0)
	v_mfma_f32_32x32x16_bf16 v[98:113], v[194:197], v[130:133], v[98:113]
	v_mfma_f32_32x32x16_bf16 v[66:81], v[194:197], v[146:149], v[66:81]
	v_mfma_f32_32x32x16_bf16 v[98:113], v[198:201], v[134:137], v[98:113]
	v_mfma_f32_32x32x16_bf16 v[66:81], v[198:201], v[150:153], v[66:81]
	v_mfma_f32_32x32x16_bf16 v[98:113], v[228:231], v[138:141], v[98:113]
	v_mfma_f32_32x32x16_bf16 v[66:81], v[228:231], v[158:161], v[66:81]
	v_mfma_f32_32x32x16_bf16 v[98:113], v[232:235], v[142:145], v[98:113]
	v_mfma_f32_32x32x16_bf16 v[66:81], v[232:235], v[162:165], v[66:81]
	s_barrier
	v_add3_u32 v166, v248, v244, s21
	v_add3_u32 v167, v248, v245, s21
	v_add3_u32 v175, v248, v246, s21
	v_add3_u32 v185, v248, v247, s21
	ds_read_b128 v[130:133], v166 offset:16384
	ds_read_b128 v[134:137], v167 offset:16384
	ds_read_b128 v[138:141], v175 offset:16384
	ds_read_b128 v[142:145], v185 offset:16384
	ds_read_b128 v[146:149], v166 offset:20480
	ds_read_b128 v[150:153], v167 offset:20480
	ds_read_b128 v[158:161], v175 offset:20480
	ds_read_b128 v[162:165], v185 offset:20480
	s_barrier
	s_waitcnt lgkmcnt(0)
	v_mfma_f32_32x32x16_bf16 v[50:65], v[176:179], v[130:133], v[50:65]
	v_mfma_f32_32x32x16_bf16 v[18:33], v[176:179], v[146:149], v[18:33]
	v_mfma_f32_32x32x16_bf16 v[50:65], v[180:183], v[134:137], v[50:65]
	v_mfma_f32_32x32x16_bf16 v[18:33], v[180:183], v[150:153], v[18:33]
	v_mfma_f32_32x32x16_bf16 v[50:65], v[186:189], v[138:141], v[50:65]
	v_mfma_f32_32x32x16_bf16 v[18:33], v[186:189], v[158:161], v[18:33]
	v_mfma_f32_32x32x16_bf16 v[50:65], v[190:193], v[142:145], v[50:65]
	v_mfma_f32_32x32x16_bf16 v[18:33], v[190:193], v[162:165], v[18:33]
	v_mfma_f32_32x32x16_bf16 v[34:49], v[194:197], v[130:133], v[34:49]
	v_mfma_f32_32x32x16_bf16 v[2:17], v[194:197], v[146:149], v[2:17]
	v_mfma_f32_32x32x16_bf16 v[34:49], v[198:201], v[134:137], v[34:49]
	v_mfma_f32_32x32x16_bf16 v[2:17], v[198:201], v[150:153], v[2:17]
	v_mfma_f32_32x32x16_bf16 v[34:49], v[228:231], v[138:141], v[34:49]
	v_mfma_f32_32x32x16_bf16 v[2:17], v[228:231], v[158:161], v[2:17]
	v_mfma_f32_32x32x16_bf16 v[34:49], v[232:235], v[142:145], v[34:49]
	v_mfma_f32_32x32x16_bf16 v[2:17], v[232:235], v[162:165], v[2:17]
	s_barrier
	s_cmp_eq_u32 s101, 0
	s_cbranch_scc0 .Lg8_u0_p1
	s_barrier

; template <int EPI>
; DI void phase_gemm(const Params& p, const GemmArgs& ga, char* lds) {
;     ...
;     } else {
;       __syncthreads();
;       constexpr int RS = 520;
;       {
;         char* wbase = lds + (wm * 128 + r) * RS + (wn * 64 + 4 * h) * 2;
; #pragma unroll
;         for (int mi = 0; mi < 4; ++mi)
; #pragma unroll
;           for (int ni = 0; ni < 2; ++ni)
; #pragma unroll
;             for (int j = 0; j < 4; ++j) {
;               u32x2 v = {pk_bf16(acc[mi][ni][4 * j], acc[mi][ni][4 * j + 1]), pk_bf16(acc[mi][ni][4 * j + 2], acc[mi][ni][4 * j + 3])};
;               *(u32x2*)(wbase + mi * 32 * RS + (ni * 32 + 8 * j) * 2) = v;
;             }
;       }
;       __syncthreads();
;       {
;         const int q4 = tid & 31, seg = tid >> 5;
;         const int ch = nt * 128 + 4 * q4;
;         const float* cw = p.ffn_conv_w + (size_t)ga.layer * 3 * 5632;
;         const float* cb = p.ffn_conv_b + (size_t)ga.layer * 5632;
;         float4 wg[3], wv[3];
; #pragma unroll
;         for (int t3 = 0; t3 < 3; ++t3) { wg[t3] = *(const float4*)(cw + t3 * 5632 + ch); wv[t3] = *(const float4*)(cw + t3 * 5632 + DFF + ch); }
;         const float4 bg = *(const float4*)(cb + ch);
;         const float4 bv = *(const float4*)(cb + DFF + ch);
;         const char* gbase = lds + q4 * 8;
;         const char* vbase = lds + 256 + q4 * 8;
;         const int R0 = 1 + seg * 16;
;         const int Rend = (R0 + 16 < 255) ? (R0 + 16) : 255;
;         auto ld4 = [&](const char* b_, int R) -> float4 {
;           const u32x2 u = *(const u32x2*)(b_ + R * RS);
;           float4 f = {__uint_as_float(u.x << 16), __uint_as_float(u.x & 0xffff0000u), __uint_as_float(u.y << 16), __uint_as_float(u.y & 0xffff0000u)};
;           return f;
;         };
;         float4 pg = ld4(gbase, R0 - 1), pvv = ld4(vbase, R0 - 1);
;         float4 cg_ = ld4(gbase, R0), cv_ = ld4(vbase, R0);
.LBB0_61:
	v_add_u32_e32 v0, 0x4000, v173
	s_barrier
	s_nop 8
	v_cvt_pk_bf16_f32 v82, v82, v83
	v_cvt_pk_bf16_f32 v83, v84, v85
	v_cvt_pk_bf16_f32 v84, v86, v87
	v_cvt_pk_bf16_f32 v85, v88, v89
	ds_write2_b64 v0, v[82:83], v[84:85] offset0:32 offset1:34
	v_cvt_pk_bf16_f32 v82, v90, v91
	v_cvt_pk_bf16_f32 v83, v92, v93
	v_cvt_pk_bf16_f32 v66, v66, v67
	v_cvt_pk_bf16_f32 v67, v68, v69
	v_cvt_pk_bf16_f32 v68, v70, v71
	v_cvt_pk_bf16_f32 v69, v72, v73
	v_cvt_pk_bf16_f32 v84, v94, v95
	v_cvt_pk_bf16_f32 v85, v96, v97
	ds_write2_b64 v0, v[66:67], v[68:69] offset0:40 offset1:42
	v_cvt_pk_bf16_f32 v66, v74, v75
	v_cvt_pk_bf16_f32 v67, v76, v77
	v_cvt_pk_bf16_f32 v68, v78, v79
	v_cvt_pk_bf16_f32 v69, v80, v81
	ds_write2_b64 v0, v[82:83], v[84:85] offset0:36 offset1:38
	ds_write2_b64 v0, v[66:67], v[68:69] offset0:44 offset1:46
	v_cvt_pk_bf16_f32 v50, v50, v51
	v_cvt_pk_bf16_f32 v51, v52, v53
	v_cvt_pk_bf16_f32 v52, v54, v55
	v_cvt_pk_bf16_f32 v53, v56, v57
	v_add_u32_e32 v0, 0x8000, v173
	v_cvt_pk_bf16_f32 v34, v34, v35
	v_cvt_pk_bf16_f32 v35, v36, v37
	v_cvt_pk_bf16_f32 v36, v38, v39
	v_cvt_pk_bf16_f32 v37, v40, v41
	ds_write2_b64 v0, v[50:51], v[52:53] offset0:64 offset1:66
	v_cvt_pk_bf16_f32 v50, v58, v59
	v_cvt_pk_bf16_f32 v51, v60, v61
	v_cvt_pk_bf16_f32 v52, v62, v63
	v_cvt_pk_bf16_f32 v53, v64, v65
	ds_write2_b64 v0, v[34:35], v[36:37] offset0:72 offset1:74
	v_cvt_pk_bf16_f32 v34, v42, v43
	v_cvt_pk_bf16_f32 v35, v44, v45
	v_cvt_pk_bf16_f32 v36, v46, v47
	v_cvt_pk_bf16_f32 v37, v48, v49
	v_cvt_pk_bf16_f32 v114, v114, v115
	v_cvt_pk_bf16_f32 v115, v116, v117
	v_cvt_pk_bf16_f32 v116, v118, v119
	v_cvt_pk_bf16_f32 v117, v120, v121
	v_cvt_pk_bf16_f32 v98, v98, v99
	v_cvt_pk_bf16_f32 v99, v100, v101
	v_cvt_pk_bf16_f32 v100, v102, v103
	v_cvt_pk_bf16_f32 v101, v104, v105
	ds_write2_b64 v0, v[50:51], v[52:53] offset0:68 offset1:70
	ds_write2_b64 v0, v[34:35], v[36:37] offset0:76 offset1:78
	v_cvt_pk_bf16_f32 v18, v18, v19
	v_cvt_pk_bf16_f32 v19, v20, v21
	v_cvt_pk_bf16_f32 v20, v22, v23
	v_cvt_pk_bf16_f32 v21, v24, v25
	v_add_u32_e32 v0, 0xc000, v173
	v_cvt_pk_bf16_f32 v2, v2, v3
	v_cvt_pk_bf16_f32 v3, v4, v5
	v_cvt_pk_bf16_f32 v4, v6, v7
	v_cvt_pk_bf16_f32 v5, v8, v9
	ds_write2_b64 v173, v[114:115], v[116:117] offset1:2
	v_cvt_pk_bf16_f32 v114, v122, v123
	v_cvt_pk_bf16_f32 v115, v124, v125
	v_cvt_pk_bf16_f32 v116, v126, v127
	v_cvt_pk_bf16_f32 v117, v128, v129
	ds_write2_b64 v173, v[98:99], v[100:101] offset0:8 offset1:10
	v_cvt_pk_bf16_f32 v98, v106, v107
	v_cvt_pk_bf16_f32 v99, v108, v109
	v_cvt_pk_bf16_f32 v100, v110, v111
	v_cvt_pk_bf16_f32 v101, v112, v113
	ds_write2_b64 v0, v[18:19], v[20:21] offset0:96 offset1:98
	v_cvt_pk_bf16_f32 v18, v26, v27
	v_cvt_pk_bf16_f32 v19, v28, v29
	v_cvt_pk_bf16_f32 v20, v30, v31
	v_cvt_pk_bf16_f32 v21, v32, v33
	ds_write2_b64 v0, v[2:3], v[4:5] offset0:104 offset1:106
	v_cvt_pk_bf16_f32 v2, v10, v11
	v_cvt_pk_bf16_f32 v3, v12, v13
	v_cvt_pk_bf16_f32 v4, v14, v15
	v_cvt_pk_bf16_f32 v5, v16, v17
	ds_write2_b64 v173, v[114:115], v[116:117] offset0:4 offset1:6
	ds_write2_b64 v173, v[98:99], v[100:101] offset0:12 offset1:14
	ds_write2_b64 v0, v[18:19], v[20:21] offset0:100 offset1:102
	ds_write2_b64 v0, v[2:3], v[4:5] offset0:108 offset1:110
	s_waitcnt lgkmcnt(0)
	s_barrier
	s_and_saveexec_b64 s[12:13], vcc
	s_cbranch_execz .LBB0_54
	v_lshl_or_b32 v42, s28, 7, v157
	v_ashrrev_i32_e32 v43, 31, v42
	v_readlane_b32 s10, v253, 19
	v_lshlrev_b64 v[2:3], 2, v[42:43]
	v_readlane_b32 s11, v253, 20
	v_mov_b32_e32 v0, v169
	s_nop 0
	v_lshl_add_u64 v[4:5], s[10:11], 0, v[2:3]
	v_readlane_b32 s10, v253, 21
	v_readlane_b32 s11, v253, 22
	s_nop 1
	v_lshl_add_u64 v[6:7], s[10:11], 0, v[2:3]
	v_readlane_b32 s10, v253, 23
	v_readlane_b32 s11, v253, 24
	s_nop 1
	v_lshl_add_u64 v[10:11], s[10:11], 0, v[2:3]
	v_readlane_b32 s10, v253, 25
	v_readlane_b32 s11, v253, 26
	s_nop 1
	v_lshl_add_u64 v[14:15], s[10:11], 0, v[2:3]
	v_readlane_b32 s10, v253, 27
	v_readlane_b32 s11, v253, 28
	s_nop 1
	v_lshl_add_u64 v[18:19], s[10:11], 0, v[2:3]
	v_readlane_b32 s10, v253, 29
	v_readlane_b32 s11, v253, 30
	s_nop 1
	v_lshl_add_u64 v[22:23], s[10:11], 0, v[2:3]
	v_readlane_b32 s10, v253, 31
	v_readlane_b32 s11, v253, 32
	s_nop 1
	v_lshl_add_u64 v[26:27], s[10:11], 0, v[2:3]
	v_readlane_b32 s10, v253, 33
	v_readlane_b32 s11, v253, 34
	s_nop 1
	v_lshl_add_u64 v[30:31], s[10:11], 0, v[2:3]
	global_load_dwordx4 v[2:5], v[4:5], off
	s_nop 0
	global_load_dwordx4 v[6:9], v[6:7], off
	s_nop 0
	global_load_dwordx4 v[10:13], v[10:11], off
	s_nop 0
	global_load_dwordx4 v[14:17], v[14:15], off
	s_nop 0
	global_load_dwordx4 v[18:21], v[18:19], off
	s_nop 0
	global_load_dwordx4 v[22:25], v[22:23], off
	s_nop 0
	global_load_dwordx4 v[26:29], v[26:27], off
	s_nop 0
	global_load_dwordx4 v[30:33], v[30:31], off
	ds_read2_b64 v[36:39], v174 offset0:65 offset1:97
	ds_read2_b64 v[46:49], v174 offset1:32
	s_waitcnt lgkmcnt(1)
	v_and_b32_e32 v35, 0xffff0000, v37
	v_lshlrev_b32_e32 v34, 16, v37
	v_and_b32_e32 v41, 0xffff0000, v36
	v_lshlrev_b32_e32 v40, 16, v36
	v_lshlrev_b32_e32 v36, 16, v39
	v_and_b32_e32 v37, 0xffff0000, v39
	s_waitcnt lgkmcnt(0)
	v_lshlrev_b32_e32 v50, 16, v49
	v_and_b32_e32 v51, 0xffff0000, v49
	v_lshlrev_b32_e32 v52, 16, v47
	v_and_b32_e32 v53, 0xffff0000, v47
	v_lshlrev_b32_e32 v44, 16, v38
	v_and_b32_e32 v45, 0xffff0000, v38
	v_lshlrev_b32_e32 v54, 16, v48
	v_and_b32_e32 v55, 0xffff0000, v48
	v_lshlrev_b32_e32 v56, 16, v46
	v_and_b32_e32 v57, 0xffff0000, v46
	v_lshlrev_b64 v[46:47], 1, v[42:43]
	s_and_saveexec_b64 s[14:15], s[6:7]
	s_cbranch_execz .LBB0_68
	s_add_i32 s10, s27, -2
	v_mad_i64_i32 v[38:39], s[10:11], s10, v216, v[46:47]
	v_lshl_add_u64 v[38:39], v[154:155], 0, v[38:39]
	s_mov_b64 s[16:17], 0
	v_mov_b32_e32 v0, v171
	v_mov_b32_e32 v62, v172
	v_mov_b32_e32 v64, v168
	s_mov_b64 s[22:23], 0x1600
	s_waitcnt vmcnt(0)
	s_branch .LBB0_65

; template <bool SWAP>
; DI void gemm_mainloop(f32x16 (&acc)[4][2], const u16* __restrict__ A, int lda, int rlo, int rhi,
;                       const u16* __restrict__ B, int ldb, int K, char* lds, const u16* zero_line) {
;     ...
;   const int gch = (lc ^ ((lr >> 1) & 7)) * 8;
;   const u16* ap = A + (ptrdiff_t)lr * lda + gch;
;   const u16* bp = B + (ptrdiff_t)lr * ldb + gch;
;   const int nk = K >> 6;
;   typedef __attribute__((address_space(3))) unsigned lds_u32;
;   auto glds = [&](int kt, int st) {
;     char* as_ = lds + st * 65536 + tid * 16;
; #pragma unroll
;     for (int i = 0; i < 4; ++i) {
;       const int rr = lr + 64 * i;
;       const u16* srca = (rr >= rlo && rr < rhi) ? (ap + (ptrdiff_t)(64 * i) * lda + kt * 64) : (zero_line + lc * 8);
;       __builtin_amdgcn_global_load_lds((const unsigned*)srca, (lds_u32*)(as_ + i * 8192), 16, 0, 0);
;       __builtin_amdgcn_global_load_lds((const unsigned*)(bp + (ptrdiff_t)(64 * i) * ldb + kt * 64), (lds_u32*)(as_ + 32768 + i * 8192), 16, 0, 0);
;     }
;   };
;   const int sw = (r >> 1) & 7;
;   const int arow_off = (wm * 128 + r) * 128;
;   const int brow_off = 32768 + (wn * 64 + r) * 128;
;   __syncthreads();
;   glds(0, 0);
;   asm volatile("s_waitcnt vmcnt(0)" ::: "memory");
;   __syncthreads();
; template <int EPI>
; DI void phase_gemm(const Params& p, const GemmArgs& ga, char* lds) {
;     ...
;   for (int it = 0; it * (int)gridDim.x < total; ++it) {
;     const int lt = logical_index(it);
;     if (lt >= total) continue;
;     int mt, nt;
;     tile_mn(lt, Mt, ga.Nt, mt, nt);
;     int bb, tokbase, S, pos0, rlo = 0, rhi = 256;
;     if (EPI == EPI_UP) {
;       bb = 0; tokbase = 0; S = NTOK;
;       pos0 = 254 * mt - 1;
;       rlo = (mt == 0) ? 1 : 0;
;       rhi = NTOK - pos0; if (rhi > 256) rhi = 256;
;     } else {
;       seq_of_token(mt * 256, bb, tokbase, S);
;       pos0 = mt * 256 - tokbase;
;     }
;     const u16* A = ga.A + (ptrdiff_t)(tokbase + pos0) * ga.lda;
;     const u16* B = ga.Bt + (size_t)(nt * 256) * ga.K;
.LBB0_167:
	s_add_i32 s30, s10, s25
	s_cmpk_gt_i32 s30, 0x10ab
	s_cbranch_scc1 .LBB0_166
	s_mul_hi_i32 s10, s30, 0x2e8ba2e9
	s_lshr_b32 s11, s10, 31
	s_ashr_i32 s10, s10, 5
	s_add_i32 s31, s10, s11
	s_lshl_b32 s10, s31, 3
	s_sub_i32 s11, 0xc2, s10
	s_min_u32 s11, s11, 8
	v_cvt_f32_ubyte0_e32 v0, s11
	v_rcp_iflag_f32_e32 v0, v0
	s_sub_i32 s15, 0, s11
	s_mul_i32 s12, s31, 0xffffff50
	s_add_i32 s12, s12, s30
	v_mul_f32_e32 v0, 0x4f7ffffe, v0
	v_cvt_u32_f32_e32 v0, v0
	s_abs_i32 s14, s12
	s_ashr_i32 s13, s12, 31
	s_waitcnt vmcnt(5)
	v_mov_b32_e32 v13, v204
	v_readfirstlane_b32 s16, v0
	s_mul_i32 s15, s15, s16
	s_mul_hi_u32 s15, s16, s15
	s_add_i32 s16, s16, s15
	s_mul_hi_u32 s15, s14, s16
	s_mul_i32 s16, s15, s11
	s_sub_i32 s14, s14, s16
	s_add_i32 s16, s15, 1
	s_sub_i32 s17, s14, s11
	s_cmp_ge_u32 s14, s11
	s_cselect_b32 s15, s16, s15
	s_cselect_b32 s14, s17, s14
	s_add_i32 s16, s15, 1
	s_cmp_ge_u32 s14, s11
	s_cselect_b32 s14, s16, s15
	s_xor_b32 s14, s14, s13
	s_sub_i32 s28, s14, s13
	s_mul_i32 s34, s28, s11
	s_add_i32 s14, s12, s10
	s_sub_i32 s27, s14, s34
	s_mulk_i32 s27, 0xfe
	s_lshl_b32 s10, s28, 8
	s_add_i32 s20, s27, -1
	s_ashr_i32 s11, s10, 31
	s_ashr_i32 s21, s20, 31
	s_lshl_b64 s[22:23], s[10:11], 11
	v_readlane_b32 s10, v253, 47
	v_readlane_b32 s11, v253, 48
	s_add_u32 s10, s10, s22
	s_addc_u32 s11, s11, s23
	s_lshl_b64 s[12:13], s[20:21], 11
	s_add_u32 s12, s90, s12
	v_ashrrev_i32_e32 v2, 3, v13
	s_waitcnt vmcnt(4)
	v_lshrrev_b32_e32 v15, 1, v2
	s_addc_u32 s13, s91, s13
	s_sub_i32 s15, 0xc001, s27
	v_xor_b32_e32 v0, v15, v13
	v_ashrrev_i32_e32 v3, 31, v2
	s_min_i32 s18, s15, 0x100
	v_lshlrev_b64 v[4:5], 11, v[2:3]
	v_lshlrev_b32_e32 v0, 4, v0
	s_cmp_eq_u32 s14, s34
	v_and_b32_e32 v10, 31, v13
	v_lshl_add_u64 v[6:7], s[12:13], 0, v[4:5]
	v_and_b32_e32 v0, 0x70, v0
	v_lshl_add_u64 v[8:9], s[10:11], 0, v[4:5]
	v_lshrrev_b32_e32 v16, 1, v13
	s_cselect_b64 s[14:15], -1, 0
	v_lshl_add_u64 v[6:7], v[6:7], 0, v[0:1]
	v_lshl_add_u64 v[8:9], v[8:9], 0, v[0:1]
	v_and_or_b32 v0, v16, s51, v10
	v_cndmask_b32_e64 v12, 0, 1, s[14:15]
	v_lshlrev_b32_e32 v175, 7, v0
	v_lshlrev_b32_e32 v0, 7, v13
	v_lshlrev_b32_e32 v177, 4, v13
	v_and_b32_e32 v176, 0x6f80, v0
	v_cmp_ge_i32_e64 s[10:11], v2, v12
	v_cmp_gt_i32_e64 s[12:13], s18, v2
	v_and_b32_e32 v0, 0x70, v177
	v_add_u32_e32 v178, 0x8000, v177
	v_lshl_add_u64 v[158:159], s[80:81], 0, v[0:1]
	s_and_b64 s[10:11], s[10:11], s[12:13]
	v_readfirstlane_b32 s12, v177
	v_cndmask_b32_e64 v11, v159, v7, s[10:11]
	v_cndmask_b32_e64 v10, v158, v6, s[10:11]
	s_mov_b32 m0, s12
	v_readfirstlane_b32 s12, v178
	v_add_u32_e32 v0, 64, v2
	s_barrier
	s_mov_b32 m0, s12
	v_cmp_ge_i32_e64 s[12:13], v0, v12
	v_cmp_gt_i32_e64 s[14:15], s18, v0
	s_mov_b64 s[16:17], 0x20000
	v_add_u32_e32 v0, 0x2000, v177
	v_lshl_add_u64 v[10:11], v[6:7], 0, s[16:17]
	s_and_b64 s[12:13], s[12:13], s[14:15]
	v_readfirstlane_b32 s14, v0
	v_add_u32_e32 v179, 0xa000, v177
	v_cndmask_b32_e64 v11, v159, v11, s[12:13]
	v_cndmask_b32_e64 v10, v158, v10, s[12:13]
	s_mov_b32 m0, s14
	v_readfirstlane_b32 s14, v179
	v_add_u32_e32 v3, 0x80, v2
	v_lshl_add_u64 v[10:11], v[8:9], 0, s[16:17]
	s_mov_b32 m0, s14
	v_cmp_ge_i32_e64 s[14:15], v3, v12
	v_cmp_gt_i32_e64 s[16:17], s18, v3
	s_mov_b64 s[36:37], 0x40000
	v_add_u32_e32 v180, 0x4000, v177
	v_lshl_add_u64 v[10:11], v[6:7], 0, s[36:37]
	s_and_b64 s[14:15], s[14:15], s[16:17]
	v_readfirstlane_b32 s16, v180
	v_add_u32_e32 v181, 0xc000, v177
	v_cndmask_b32_e64 v11, v159, v11, s[14:15]
	v_cndmask_b32_e64 v10, v158, v10, s[14:15]
	s_mov_b32 m0, s16
	v_readfirstlane_b32 s16, v181
	v_add_u32_e32 v2, 0xc0, v2
	v_lshl_add_u64 v[10:11], v[8:9], 0, s[36:37]
	s_mov_b32 m0, s16
	v_cmp_ge_i32_e64 s[16:17], v2, v12
	v_cmp_gt_i32_e64 s[18:19], s18, v2
	s_mov_b64 s[36:37], 0x60000
	v_add_u32_e32 v182, 0x6000, v177
	v_lshl_add_u64 v[2:3], v[6:7], 0, s[36:37]
	s_and_b64 s[16:17], s[16:17], s[18:19]
	v_readfirstlane_b32 s18, v182
	v_add_u32_e32 v183, 0xe000, v177
	v_cndmask_b32_e64 v3, v159, v3, s[16:17]
	v_cndmask_b32_e64 v2, v158, v2, s[16:17]
	s_mov_b32 m0, s18
	v_readfirstlane_b32 s18, v183
	v_lshl_add_u64 v[2:3], v[8:9], 0, s[36:37]
	s_mov_b32 m0, s18
	s_sub_i32 s18, s30, s34
	s_mulk_i32 s31, 0xa8
	v_bfe_u32 v14, v13, 5, 1
	s_sub_i32 s18, s18, s31
	v_bfe_u32 v17, v13, 1, 3
	v_bitop3_b32 v2, v16, v14, 7 bitop3:0x6c
	s_mulk_i32 s18, 0xfe
	v_lshlrev_b32_e32 v185, 4, v2
	v_bitop3_b32 v2, v14, v17, 2 bitop3:0x36
	s_add_i32 s18, s18, -2
	v_lshlrev_b32_e32 v186, 4, v2
	v_bitop3_b32 v2, v14, v17, 4 bitop3:0x36
	s_ashr_i32 s19, s18, 31
	v_lshlrev_b32_e32 v187, 4, v2
	v_bitop3_b32 v2, v14, v17, 6 bitop3:0x36
	s_lshl_b64 s[18:19], s[18:19], 11
	v_bitop3_b32 v6, v15, 7, v13 bitop3:0x48
	v_lshlrev_b32_e32 v188, 4, v2
	v_lshl_add_u64 v[2:3], v[4:5], 0, s[18:19]
	v_lshlrev_b32_e32 v6, 4, v6
	v_or_b32_e32 v2, v2, v6
	v_lshl_add_u64 v[160:161], s[70:71], 0, v[2:3]
	v_lshl_add_u64 v[2:3], v[4:5], 0, s[22:23]
	s_waitcnt vmcnt(0)
	v_or_b32_e32 v2, v2, v6
	v_lshl_add_u64 v[162:163], s[70:71], 0, v[2:3]
	v_mov_b32_e32 v130, 0
	v_mov_b32_e32 v2, 0
	s_mov_b32 s29, 1
	v_add_u32_e32 v189, 0x10000, v177
	v_add_u32_e32 v190, 0x18000, v177
	v_add_u32_e32 v191, 0x12000, v177
	v_add_u32_e32 v192, 0x1a000, v177
	v_add_u32_e32 v193, 0x14000, v177
	v_add_u32_e32 v194, 0x1c000, v177
	v_add_u32_e32 v195, 0x16000, v177
	v_add_u32_e32 v196, 0x1e000, v177
	v_add_u32_e32 v197, 0x10000, v175
	v_or_b32_e32 v198, 0x10000, v176
	s_mov_b64 s[18:19], 0
	v_mov_b32_e32 v3, v2
	v_mov_b32_e32 v4, v2
	v_mov_b32_e32 v5, v2
	v_mov_b32_e32 v6, v2
	v_mov_b32_e32 v7, v2
	v_mov_b32_e32 v8, v2
	v_mov_b32_e32 v9, v2
	v_mov_b32_e32 v10, v2
	v_mov_b32_e32 v11, v2
	v_mov_b32_e32 v12, v2
	v_mov_b32_e32 v13, v2
	v_mov_b32_e32 v14, v2
	v_mov_b32_e32 v15, v2
	v_mov_b32_e32 v16, v2
	v_mov_b32_e32 v17, v2
	s_waitcnt vmcnt(0)
; template <bool SWAP>
; DI void gemm_mainloop(f32x16 (&acc)[4][2], const u16* __restrict__ A, int lda, int rlo, int rhi,
;                       const u16* __restrict__ B, int ldb, int K, char* lds, const u16* zero_line) {
;     ...
; #pragma unroll
;   for (int mi = 0; mi < 4; ++mi)
; #pragma unroll
;     for (int ni = 0; ni < 2; ++ni)
; #pragma unroll
;       for (int i = 0; i < 16; ++i) acc[mi][ni][i] = 0.f;
;   const int gch = (lc ^ ((lr >> 1) & 7)) * 8;
;   const u16* ap = A + (ptrdiff_t)lr * lda + gch;
;   const u16* bp = B + (ptrdiff_t)lr * ldb + gch;
;   const int nk = K >> 6;
;   typedef __attribute__((address_space(3))) unsigned lds_u32;
;   auto glds = [&](int kt, int st) {
;     char* as_ = lds + st * 65536 + tid * 16;
; #pragma unroll
;     for (int i = 0; i < 4; ++i) {
;       const int rr = lr + 64 * i;
;       const u16* srca = (rr >= rlo && rr < rhi) ? (ap + (ptrdiff_t)(64 * i) * lda + kt * 64) : (zero_line + lc * 8);
;       __builtin_amdgcn_global_load_lds((const unsigned*)srca, (lds_u32*)(as_ + i * 8192), 16, 0, 0);
;       __builtin_amdgcn_global_load_lds((const unsigned*)(bp + (ptrdiff_t)(64 * i) * ldb + kt * 64), (lds_u32*)(as_ + 32768 + i * 8192), 16, 0, 0);
;     }
;   };
;   const int sw = (r >> 1) & 7;
;   const int arow_off = (wm * 128 + r) * 128;
;   const int brow_off = 32768 + (wn * 64 + r) * 128;
;   __syncthreads();
;   glds(0, 0);
;   asm volatile("s_waitcnt vmcnt(0)" ::: "memory");
;   __syncthreads();
	v_mov_b32_e32 v18, v2
	v_mov_b32_e32 v19, v2
	v_mov_b32_e32 v20, v2
	v_mov_b32_e32 v21, v2
	v_mov_b32_e32 v22, v2
	v_mov_b32_e32 v23, v2
	v_mov_b32_e32 v24, v2
	v_mov_b32_e32 v25, v2
	v_mov_b32_e32 v26, v2
	v_mov_b32_e32 v27, v2
	v_mov_b32_e32 v28, v2
	v_mov_b32_e32 v29, v2
	v_mov_b32_e32 v30, v2
	v_mov_b32_e32 v31, v2
	v_mov_b32_e32 v32, v2
	v_mov_b32_e32 v33, v2
	v_mov_b32_e32 v34, v2
	v_mov_b32_e32 v35, v2
	v_mov_b32_e32 v36, v2
	v_mov_b32_e32 v37, v2
	v_mov_b32_e32 v38, v2
	v_mov_b32_e32 v39, v2
	v_mov_b32_e32 v40, v2
	v_mov_b32_e32 v41, v2
	v_mov_b32_e32 v42, v2
	v_mov_b32_e32 v43, v2
	v_mov_b32_e32 v44, v2
	v_mov_b32_e32 v45, v2
	v_mov_b32_e32 v46, v2
	v_mov_b32_e32 v47, v2
	v_mov_b32_e32 v48, v2
	v_mov_b32_e32 v49, v2
	v_mov_b32_e32 v50, v2
	v_mov_b32_e32 v51, v2
	v_mov_b32_e32 v52, v2
	v_mov_b32_e32 v53, v2
	v_mov_b32_e32 v54, v2
	v_mov_b32_e32 v55, v2
	v_mov_b32_e32 v56, v2
	v_mov_b32_e32 v57, v2
	v_mov_b32_e32 v58, v2
	v_mov_b32_e32 v59, v2
	v_mov_b32_e32 v60, v2
	v_mov_b32_e32 v61, v2
	v_mov_b32_e32 v62, v2
	v_mov_b32_e32 v63, v2
	v_mov_b32_e32 v64, v2
	v_mov_b32_e32 v65, v2
	v_mov_b32_e32 v66, v2
	v_mov_b32_e32 v67, v2
	v_mov_b32_e32 v68, v2
	v_mov_b32_e32 v69, v2
	v_mov_b32_e32 v70, v2
	v_mov_b32_e32 v71, v2
	v_mov_b32_e32 v72, v2
	v_mov_b32_e32 v73, v2
	v_mov_b32_e32 v74, v2
	v_mov_b32_e32 v75, v2
	v_mov_b32_e32 v76, v2
	v_mov_b32_e32 v77, v2
	v_mov_b32_e32 v78, v2
	v_mov_b32_e32 v79, v2
	v_mov_b32_e32 v80, v2
	v_mov_b32_e32 v81, v2
	v_mov_b32_e32 v82, v2
	v_mov_b32_e32 v83, v2
	v_mov_b32_e32 v84, v2
	v_mov_b32_e32 v85, v2
	v_mov_b32_e32 v86, v2
	v_mov_b32_e32 v87, v2
	v_mov_b32_e32 v88, v2
	v_mov_b32_e32 v89, v2
	v_mov_b32_e32 v90, v2
	v_mov_b32_e32 v91, v2
	v_mov_b32_e32 v92, v2
	v_mov_b32_e32 v93, v2
	v_mov_b32_e32 v94, v2
	v_mov_b32_e32 v95, v2
	v_mov_b32_e32 v96, v2
	v_mov_b32_e32 v97, v2
	v_mov_b32_e32 v98, v2
	v_mov_b32_e32 v99, v2
	v_mov_b32_e32 v100, v2
	v_mov_b32_e32 v101, v2
	v_mov_b32_e32 v102, v2
	v_mov_b32_e32 v103, v2
	v_mov_b32_e32 v104, v2
	v_mov_b32_e32 v105, v2
	v_mov_b32_e32 v106, v2
	v_mov_b32_e32 v107, v2
	v_mov_b32_e32 v108, v2
	v_mov_b32_e32 v109, v2
	v_mov_b32_e32 v110, v2
	v_mov_b32_e32 v111, v2
	v_mov_b32_e32 v112, v2
	v_mov_b32_e32 v113, v2
	v_mov_b32_e32 v114, v2
	v_mov_b32_e32 v115, v2
	v_mov_b32_e32 v116, v2
	v_mov_b32_e32 v117, v2
	v_mov_b32_e32 v118, v2
	v_mov_b32_e32 v119, v2
	v_mov_b32_e32 v120, v2
	v_mov_b32_e32 v121, v2
	v_mov_b32_e32 v122, v2
	v_mov_b32_e32 v123, v2
	v_mov_b32_e32 v124, v2
	v_mov_b32_e32 v125, v2
	v_mov_b32_e32 v126, v2
	v_mov_b32_e32 v127, v2
	v_mov_b32_e32 v128, v2
	v_mov_b32_e32 v129, v2
	v_mov_b32_e32 v131, v130
	v_mov_b32_e32 v132, v130
	v_mov_b32_e32 v133, v130
	v_mov_b32_e32 v134, v130
	v_mov_b32_e32 v135, v130
	v_mov_b32_e32 v136, v130
	v_mov_b32_e32 v137, v130
	v_mov_b32_e32 v138, v130
	v_mov_b32_e32 v139, v130
	v_mov_b32_e32 v140, v130
	v_mov_b32_e32 v141, v130
	v_mov_b32_e32 v142, v130
	v_mov_b32_e32 v143, v130
	v_mov_b32_e32 v144, v130
	v_mov_b32_e32 v145, v130
	v_mov_b32_e32 v146, v130
	v_mov_b32_e32 v147, v130
	v_mov_b32_e32 v148, v130
	v_mov_b32_e32 v149, v130
	v_mov_b32_e32 v150, v130
	v_mov_b32_e32 v151, v130
	v_mov_b32_e32 v152, v130
	v_mov_b32_e32 v153, v130
	s_mov_b64 s[30:31], 0x37f8900
	s_waitcnt lgkmcnt(0)
	s_barrier
	s_add_i32 s18, s27, -1
	s_ashr_i32 s19, s18, 31
	s_lshl_b64 s[18:19], s[18:19], 11
	s_add_u32 s18, s90, s18
	s_addc_u32 s19, s91, s19
	v_readlane_b32 s22, v253, 47
	v_readlane_b32 s23, v253, 48
	s_lshl_b32 s21, s28, 19
	s_add_u32 s22, s22, s21
	s_addc_u32 s23, s23, 0
	v_and_b32_e32 v130, 63, v204
	v_lshrrev_b32_e32 v131, 6, v204
	v_lshrrev_b32_e32 v132, 3, v204
	v_lshrrev_b32_e32 v0, 4, v130
	v_lshl_add_u32 v0, v131, 2, v0
	v_xor_b32_e32 v0, v0, v130
	v_and_b32_e32 v0, 7, v0
	v_lshlrev_b32_e32 v133, 4, v0
	v_lshl_add_u32 v236, v132, 11, v133
	v_add_u32_e32 v237, 0x20000, v236
	v_add_u32_e32 v238, 0x40000, v236
	v_add_u32_e32 v239, 0x60000, v236
	v_and_b32_e32 v0, 31, v132
	v_lshrrev_b32_e32 v130, 5, v132
	v_lshl_add_u32 v0, v130, 6, v0
	v_lshl_add_u32 v240, v0, 11, v133
	v_add_u32_e32 v241, 0x10000, v240
	v_add_u32_e32 v242, 0x40000, v240
	v_add_u32_e32 v243, 0x50000, v240
	v_and_b32_e32 v132, 31, v204
	v_lshrrev_b32_e32 v0, 2, v131
	v_lshl_add_u32 v0, v0, 6, v132
	v_lshlrev_b32_e32 v248, 7, v0
	v_and_b32_e32 v0, 3, v131
	v_lshl_add_u32 v0, v0, 5, v132
	v_lshlrev_b32_e32 v249, 7, v0
	v_bfe_u32 v0, v204, 5, 1
	v_bfe_u32 v130, v132, 1, 3
	v_or_b32_e32 v133, 0, v0
	v_xor_b32_e32 v133, v133, v130
	v_lshlrev_b32_e32 v244, 4, v133
	v_or_b32_e32 v133, 2, v0
	v_xor_b32_e32 v133, v133, v130
	v_lshlrev_b32_e32 v245, 4, v133
	v_or_b32_e32 v133, 4, v0
	v_xor_b32_e32 v133, v133, v130
	v_lshlrev_b32_e32 v246, 4, v133
	v_or_b32_e32 v133, 6, v0
	v_xor_b32_e32 v133, v133, v130
	v_lshlrev_b32_e32 v247, 4, v133
	v_lshlrev_b32_e32 v131, 10, v131
	s_nop 0
	v_readfirstlane_b32 s100, v131
	v_mov_b32_e32 v146, 0
	v_mov_b32_e32 v147, 0
	v_mov_b32_e32 v148, 0
	v_mov_b32_e32 v149, 0
	v_lshlrev_b32_e32 v130, 4, v204
	v_add_u32_e32 v132, 0x10000, v130
	s_not_b64 exec, s[10:11]
	ds_write_b128 v130, v[146:149]
	ds_write_b128 v132, v[146:149]
	s_not_b64 exec, s[12:13]
	ds_write_b128 v130, v[146:149] offset:16384
	ds_write_b128 v132, v[146:149] offset:16384
	s_not_b64 exec, s[14:15]
	ds_write_b128 v130, v[146:149] offset:8192
	ds_write_b128 v132, v[146:149] offset:8192
	s_not_b64 exec, s[16:17]
	ds_write_b128 v130, v[146:149] offset:24576
	ds_write_b128 v132, v[146:149] offset:24576
	s_mov_b64 exec, -1
	s_mov_b32 s29, 0
	s_mov_b32 s21, 0x10000
	s_waitcnt lgkmcnt(0)
	s_add_u32 m0, s100, 0x8000
	s_nop 0
	global_load_lds_dwordx4 v240, s[22:23]
	v_add_u32_e32 v240, 0x80, v240
	s_add_u32 m0, s100, 0xa000
	s_nop 0
	global_load_lds_dwordx4 v242, s[22:23]
	v_add_u32_e32 v242, 0x80, v242
	s_add_u32 m0, s100, 0x0
	s_mov_b64 exec, s[10:11]
	global_load_lds_dwordx4 v236, s[18:19]
	s_mov_b64 exec, -1
	v_add_u32_e32 v236, 0x80, v236
	s_add_u32 m0, s100, 0x2000
	s_mov_b64 exec, s[14:15]
	global_load_lds_dwordx4 v238, s[18:19]
	s_mov_b64 exec, -1
	v_add_u32_e32 v238, 0x80, v238
	s_add_u32 m0, s100, 0xc000
	s_nop 0
	global_load_lds_dwordx4 v241, s[22:23]
	v_add_u32_e32 v241, 0x80, v241
	s_add_u32 m0, s100, 0xe000
	s_nop 0
	global_load_lds_dwordx4 v243, s[22:23]
	v_add_u32_e32 v243, 0x80, v243
	s_add_u32 m0, s100, 0x4000
	s_mov_b64 exec, s[12:13]
	global_load_lds_dwordx4 v237, s[18:19]
	s_mov_b64 exec, -1
	v_add_u32_e32 v237, 0x80, v237
	s_add_u32 m0, s100, 0x6000
	s_mov_b64 exec, s[16:17]
	global_load_lds_dwordx4 v239, s[18:19]
	s_mov_b64 exec, -1
	v_add_u32_e32 v239, 0x80, v239
	s_cmp_eq_u32 s101, 1
	s_cbranch_scc0 .Lg8_u1_p0
	s_barrier

; template <int EPI>
; DI void phase_gemm(const Params& p, const GemmArgs& ga, char* lds) {
;     ...
;     } else {
;       __syncthreads();
;       constexpr int RS = 520;
;       {
;         char* wbase = lds + (wm * 128 + r) * RS + (wn * 64 + 4 * h) * 2;
; #pragma unroll
;         for (int mi = 0; mi < 4; ++mi)
; #pragma unroll
;           for (int ni = 0; ni < 2; ++ni)
; #pragma unroll
;             for (int j = 0; j < 4; ++j) {
;               u32x2 v = {pk_bf16(acc[mi][ni][4 * j], acc[mi][ni][4 * j + 1]), pk_bf16(acc[mi][ni][4 * j + 2], acc[mi][ni][4 * j + 3])};
;               *(u32x2*)(wbase + mi * 32 * RS + (ni * 32 + 8 * j) * 2) = v;
;             }
;       }
;       __syncthreads();
;       {
;         const int q4 = tid & 31, seg = tid >> 5;
;         const int ch = nt * 128 + 4 * q4;
;         const float* cw = p.ffn_conv_w + (size_t)ga.layer * 3 * 5632;
;         const float* cb = p.ffn_conv_b + (size_t)ga.layer * 5632;
;         float4 wg[3], wv[3];
; #pragma unroll
;         for (int t3 = 0; t3 < 3; ++t3) { wg[t3] = *(const float4*)(cw + t3 * 5632 + ch); wv[t3] = *(const float4*)(cw + t3 * 5632 + DFF + ch); }
;         const float4 bg = *(const float4*)(cb + ch);
;         const float4 bv = *(const float4*)(cb + DFF + ch);
;         const char* gbase = lds + q4 * 8;
;         const char* vbase = lds + 256 + q4 * 8;
;         const int R0 = 1 + seg * 16;
;         const int Rend = (R0 + 16 < 255) ? (R0 + 16) : 255;
;         auto ld4 = [&](const char* b_, int R) -> float4 {
;           const u32x2 u = *(const u32x2*)(b_ + R * RS);
;           float4 f = {__uint_as_float(u.x << 16), __uint_as_float(u.x & 0xffff0000u), __uint_as_float(u.y << 16), __uint_as_float(u.y & 0xffff0000u)};
;           return f;
;         };
;         float4 pg = ld4(gbase, R0 - 1), pvv = ld4(vbase, R0 - 1);
;         float4 cg_ = ld4(gbase, R0), cv_ = ld4(vbase, R0);
.LBB0_172:
	v_add_u32_e32 v0, 0x4000, v173
	s_barrier
	s_nop 8
	v_cvt_pk_bf16_f32 v82, v82, v83
	v_cvt_pk_bf16_f32 v83, v84, v85
	v_cvt_pk_bf16_f32 v84, v86, v87
	v_cvt_pk_bf16_f32 v85, v88, v89
	ds_write2_b64 v0, v[82:83], v[84:85] offset0:32 offset1:34
	v_cvt_pk_bf16_f32 v82, v90, v91
	v_cvt_pk_bf16_f32 v83, v92, v93
	v_cvt_pk_bf16_f32 v66, v66, v67
	v_cvt_pk_bf16_f32 v67, v68, v69
	v_cvt_pk_bf16_f32 v68, v70, v71
	v_cvt_pk_bf16_f32 v69, v72, v73
	v_cvt_pk_bf16_f32 v84, v94, v95
	v_cvt_pk_bf16_f32 v85, v96, v97
	ds_write2_b64 v0, v[66:67], v[68:69] offset0:40 offset1:42
	v_cvt_pk_bf16_f32 v66, v74, v75
	v_cvt_pk_bf16_f32 v67, v76, v77
	v_cvt_pk_bf16_f32 v68, v78, v79
	v_cvt_pk_bf16_f32 v69, v80, v81
	ds_write2_b64 v0, v[82:83], v[84:85] offset0:36 offset1:38
	ds_write2_b64 v0, v[66:67], v[68:69] offset0:44 offset1:46
	v_cvt_pk_bf16_f32 v50, v50, v51
	v_cvt_pk_bf16_f32 v51, v52, v53
	v_cvt_pk_bf16_f32 v52, v54, v55
	v_cvt_pk_bf16_f32 v53, v56, v57
	v_add_u32_e32 v0, 0x8000, v173
	v_cvt_pk_bf16_f32 v34, v34, v35
	v_cvt_pk_bf16_f32 v35, v36, v37
	v_cvt_pk_bf16_f32 v36, v38, v39
	v_cvt_pk_bf16_f32 v37, v40, v41
	ds_write2_b64 v0, v[50:51], v[52:53] offset0:64 offset1:66
	v_cvt_pk_bf16_f32 v50, v58, v59
	v_cvt_pk_bf16_f32 v51, v60, v61
	v_cvt_pk_bf16_f32 v52, v62, v63
	v_cvt_pk_bf16_f32 v53, v64, v65
	ds_write2_b64 v0, v[34:35], v[36:37] offset0:72 offset1:74
	v_cvt_pk_bf16_f32 v34, v42, v43
	v_cvt_pk_bf16_f32 v35, v44, v45
	v_cvt_pk_bf16_f32 v36, v46, v47
	v_cvt_pk_bf16_f32 v37, v48, v49
	v_cvt_pk_bf16_f32 v114, v114, v115
	v_cvt_pk_bf16_f32 v115, v116, v117
	v_cvt_pk_bf16_f32 v116, v118, v119
	v_cvt_pk_bf16_f32 v117, v120, v121
	v_cvt_pk_bf16_f32 v98, v98, v99
	v_cvt_pk_bf16_f32 v99, v100, v101
	v_cvt_pk_bf16_f32 v100, v102, v103
	v_cvt_pk_bf16_f32 v101, v104, v105
	ds_write2_b64 v0, v[50:51], v[52:53] offset0:68 offset1:70
	ds_write2_b64 v0, v[34:35], v[36:37] offset0:76 offset1:78
	v_cvt_pk_bf16_f32 v18, v18, v19
	v_cvt_pk_bf16_f32 v19, v20, v21
	v_cvt_pk_bf16_f32 v20, v22, v23
	v_cvt_pk_bf16_f32 v21, v24, v25
	v_add_u32_e32 v0, 0xc000, v173
	v_cvt_pk_bf16_f32 v2, v2, v3
	v_cvt_pk_bf16_f32 v3, v4, v5
	v_cvt_pk_bf16_f32 v4, v6, v7
	v_cvt_pk_bf16_f32 v5, v8, v9
	ds_write2_b64 v173, v[114:115], v[116:117] offset1:2
	v_cvt_pk_bf16_f32 v114, v122, v123
	v_cvt_pk_bf16_f32 v115, v124, v125
	v_cvt_pk_bf16_f32 v116, v126, v127
	v_cvt_pk_bf16_f32 v117, v128, v129
	ds_write2_b64 v173, v[98:99], v[100:101] offset0:8 offset1:10
	v_cvt_pk_bf16_f32 v98, v106, v107
	v_cvt_pk_bf16_f32 v99, v108, v109
	v_cvt_pk_bf16_f32 v100, v110, v111
	v_cvt_pk_bf16_f32 v101, v112, v113
	ds_write2_b64 v0, v[18:19], v[20:21] offset0:96 offset1:98
	v_cvt_pk_bf16_f32 v18, v26, v27
	v_cvt_pk_bf16_f32 v19, v28, v29
	v_cvt_pk_bf16_f32 v20, v30, v31
	v_cvt_pk_bf16_f32 v21, v32, v33
	ds_write2_b64 v0, v[2:3], v[4:5] offset0:104 offset1:106
	v_cvt_pk_bf16_f32 v2, v10, v11
	v_cvt_pk_bf16_f32 v3, v12, v13
	v_cvt_pk_bf16_f32 v4, v14, v15
	v_cvt_pk_bf16_f32 v5, v16, v17
	ds_write2_b64 v173, v[114:115], v[116:117] offset0:4 offset1:6
	ds_write2_b64 v173, v[98:99], v[100:101] offset0:12 offset1:14
	ds_write2_b64 v0, v[18:19], v[20:21] offset0:100 offset1:102
	ds_write2_b64 v0, v[2:3], v[4:5] offset0:108 offset1:110
	s_waitcnt lgkmcnt(0)
	s_barrier
	s_and_saveexec_b64 s[12:13], vcc
	s_mov_b64 s[36:37], 0x27c0080
	s_cbranch_execz .LBB0_165
	v_lshl_or_b32 v42, s28, 7, v157
	v_ashrrev_i32_e32 v43, 31, v42
	v_readlane_b32 s10, v253, 49
	v_lshlrev_b64 v[2:3], 2, v[42:43]
	v_readlane_b32 s11, v253, 50
	v_readlane_b32 s36, v254, 11
	v_readlane_b32 s37, v254, 12
	v_lshl_add_u64 v[6:7], s[10:11], 0, v[2:3]
	v_readlane_b32 s10, v253, 51
	v_readlane_b32 s11, v253, 52
	v_readlane_b32 s38, v254, 13
	v_readlane_b32 s39, v254, 14
	v_lshl_add_u64 v[10:11], s[10:11], 0, v[2:3]
	v_readlane_b32 s10, v253, 53
	v_readlane_b32 s11, v253, 54
	v_lshl_add_u64 v[4:5], s[36:37], 0, v[2:3]
	v_lshl_add_u64 v[26:27], s[38:39], 0, v[2:3]
	v_lshl_add_u64 v[14:15], s[10:11], 0, v[2:3]
	v_readlane_b32 s10, v253, 55
	v_readlane_b32 s11, v253, 56
	v_lshlrev_b64 v[46:47], 1, v[42:43]
	v_mov_b32_e32 v0, v169
	v_lshl_add_u64 v[18:19], s[10:11], 0, v[2:3]
	v_readlane_b32 s10, v253, 57
	v_readlane_b32 s11, v253, 58
	v_readlane_b32 s40, v254, 15
	v_readlane_b32 s41, v254, 16
	v_lshl_add_u64 v[22:23], s[10:11], 0, v[2:3]
	v_readlane_b32 s10, v253, 59
	v_readlane_b32 s11, v253, 60
	v_readlane_b32 s42, v254, 17
	v_readlane_b32 s43, v254, 18
	v_lshl_add_u64 v[30:31], s[10:11], 0, v[2:3]
	global_load_dwordx4 v[2:5], v[4:5], off
	s_nop 0
	global_load_dwordx4 v[6:9], v[6:7], off
	s_nop 0
	global_load_dwordx4 v[10:13], v[10:11], off
	s_nop 0
	global_load_dwordx4 v[14:17], v[14:15], off
	s_nop 0
	global_load_dwordx4 v[18:21], v[18:19], off
	s_nop 0
	global_load_dwordx4 v[22:25], v[22:23], off
	s_nop 0
	global_load_dwordx4 v[26:29], v[26:27], off
	s_nop 0
	global_load_dwordx4 v[30:33], v[30:31], off
	ds_read2_b64 v[36:39], v174 offset0:65 offset1:97
	ds_read2_b64 v[58:61], v174 offset1:32
	s_waitcnt lgkmcnt(1)
	v_and_b32_e32 v35, 0xffff0000, v37
	v_lshlrev_b32_e32 v34, 16, v37
	v_and_b32_e32 v41, 0xffff0000, v36
	v_lshlrev_b32_e32 v40, 16, v36
	v_lshlrev_b32_e32 v36, 16, v39
	v_and_b32_e32 v37, 0xffff0000, v39
	s_waitcnt lgkmcnt(0)
	v_lshlrev_b32_e32 v48, 16, v61
	v_and_b32_e32 v49, 0xffff0000, v61
	v_lshlrev_b32_e32 v52, 16, v59
	v_and_b32_e32 v53, 0xffff0000, v59
	v_lshlrev_b32_e32 v44, 16, v38
	v_and_b32_e32 v45, 0xffff0000, v38
	v_lshlrev_b32_e32 v54, 16, v60
	v_and_b32_e32 v55, 0xffff0000, v60
	v_lshlrev_b32_e32 v56, 16, v58
	v_and_b32_e32 v57, 0xffff0000, v58
	s_and_saveexec_b64 s[14:15], s[6:7]
	s_cbranch_execz .LBB0_179
	s_add_i32 s10, s27, -2
	v_mad_i64_i32 v[38:39], s[10:11], s10, v216, v[46:47]
	v_lshl_add_u64 v[38:39], v[154:155], 0, v[38:39]
	s_mov_b64 s[16:17], 0
	v_mov_b32_e32 v0, v171
	v_mov_b32_e32 v62, v172
	v_mov_b32_e32 v64, v168
	s_mov_b64 s[22:23], 0x1600
	s_waitcnt vmcnt(0)
	s_branch .LBB0_176
